# v063 + GEMM-phase seams: arrival atomic issued before the phase setup, rest of the barrier protocol right before the first LDS-DMA load
# speedup vs baseline: 1.0066x; 1.0057x over previous
_Z10fwd_kernel4Args:
	s_load_dword s33, s[0:1], 0xc8
	s_load_dwordx8 s[36:43], s[0:1], 0xa8
	s_add_u32 s30, s0, 0xc0
	v_and_b32_e32 v1, 0x3ff, v0
	v_mov_b32_e32 v239, 0
	s_addc_u32 s31, s1, 0
	s_mov_b32 s3, 0
	s_mov_b32 s32, 0
	v_cmp_eq_u32_e64 s[26:27], 0, v1
	s_and_saveexec_b64 s[4:5], s[26:27]
	s_cbranch_execz .LBB0_2
	s_add_i32 s6, 0, 0x257f0
	v_mov_b32_e32 v2, 0
	v_mov_b32_e32 v3, s6
	s_add_i32 s6, 0, 0x257f4
	ds_write_b32 v3, v2
	v_mov_b32_e32 v3, s6
	ds_write_b32 v3, v2

.LBB0_52:
	s_load_dwordx2 s[10:11], s[0:1], 0x0
	s_load_dwordx2 s[12:13], s[0:1], 0x10
	s_cmp_gt_i32 s41, 1
	s_cselect_b64 s[4:5], -1, 0
	s_and_b64 s[6:7], s[8:9], s[4:5]
	s_andn2_b64 vcc, exec, s[6:7]
	s_cbranch_vccnz .LBB0_102
	s_waitcnt vmcnt(0)
	s_waitcnt lgkmcnt(0)
	s_barrier
	s_and_saveexec_b64 s[6:7], s[26:27]
	s_cbranch_execz .LBB0_101
	v_add_u32_e32 v239, 1, v239
	s_add_i32 s8, 0, 0x257f0
	v_mov_b32_e32 v2, s8
	s_waitcnt vmcnt(0) expcnt(0) lgkmcnt(0)
	ds_read_b32 v4, v2
	s_add_i32 s8, 0, 0x257f4
	v_mov_b32_e32 v2, s8
	ds_read_b32 v2, v2
	s_waitcnt lgkmcnt(1)
	v_cmp_ne_u32_e32 vcc, 0, v4
	s_cbranch_vccnz .LBB0_69
	s_add_u32 s8, s38, 0x1d6c2200
	s_addc_u32 s9, s39, 0
	s_add_u32 s14, s38, 0x1d6c2400
	s_addc_u32 s15, s39, 0
	s_add_u32 s16, s38, 0x1d6c2500
	s_addc_u32 s17, s39, 0
	s_add_u32 s18, s38, 0x1d6c2600
	s_addc_u32 s19, s39, 0
	s_add_u32 s20, s38, 0x1d6c2700
	s_addc_u32 s21, s39, 0
	s_add_u32 s22, s38, 0x1d6c2800
	s_addc_u32 s23, s39, 0
	s_add_u32 s24, s38, 0x1d6c2900
	s_addc_u32 s25, s39, 0
	s_add_u32 s28, s38, 0x1d6c2a00
	s_addc_u32 s29, s39, 0
	s_add_u32 s44, s38, 0x1d6c2b00
	s_addc_u32 s45, s39, 0
	s_add_u32 s46, s38, 0x1d6c2c00
	s_addc_u32 s47, s39, 0
	s_add_u32 s48, s38, 0x1d6c2d00
	s_addc_u32 s49, s39, 0
	s_add_u32 s50, s38, 0x1d6c2e00
	s_addc_u32 s51, s39, 0
	s_add_u32 s52, s38, 0x1d6c2f00
	s_addc_u32 s53, s39, 0
	s_add_u32 s54, s38, 0x1d6c3000
	s_addc_u32 s55, s39, 0
	s_add_u32 s56, s38, 0x1d6c3100
	s_addc_u32 s57, s39, 0
	s_add_u32 s58, s38, 0x1d6c3200
	s_addc_u32 s59, s39, 0
	s_mul_i32 s68, s43, s33
	s_add_u32 s60, s38, 0x1d6c3300
	s_mul_i32 s68, s68, s42
	s_addc_u32 s61, s39, 0
	s_mov_b32 s69, 1
	v_mov_b32_e32 v18, 0
	s_branch .LBB0_57

.LBB0_106:
	s_cmp_gt_i32 s41, 2
	s_cselect_b64 s[4:5], -1, 0
	s_and_b64 s[6:7], s[8:9], s[4:5]
	s_andn2_b64 vcc, exec, s[6:7]
	s_cbranch_vccnz .LBB0_156
	s_waitcnt vmcnt(0)
	s_waitcnt lgkmcnt(0)
	s_barrier
	s_and_saveexec_b64 s[6:7], s[26:27]
	s_cbranch_execz .Lmy_aa_1
	s_lshl_b32 s8, s3, 8
	s_add_u32 s8, s34, s8
	s_addc_u32 s9, s35, 0
	v_mov_b32_e32 v237, 0x1000
	v_mov_b32_e32 v236, 1
	global_atomic_add v236, v237, v236, s[8:9] offset:1024 sc0
.Lmy_aa_1:
	s_or_b64 exec, exec, s[6:7]
.LBB0_156:
	s_cmp_lt_i32 s40, 3
	s_cselect_b64 s[6:7], -1, 0
	s_and_b64 s[8:9], s[6:7], s[4:5]
	s_andn2_b64 vcc, exec, s[8:9]
	s_cbranch_vccnz .LBB0_233
	s_and_saveexec_b64 s[4:5], s[26:27]
	s_cbranch_execz .LBB0_159
	s_add_u32 s14, s38, 0x53c2000
	s_addc_u32 s15, s39, 0
	s_add_u32 s6, s38, 0x97c2000
	s_addc_u32 s7, s39, 0
	s_add_i32 s16, 0, 0x20000
	v_mov_b32_e32 v2, s14
	v_mov_b32_e32 v3, s15
	v_mov_b32_e32 v4, s38
	v_mov_b32_e32 v5, s39
	v_mov_b32_e32 v6, s16
	s_mov_b32 s14, 0
	ds_write_b128 v6, v[2:5]
	s_add_i32 s16, 0, 0x20010
	v_mov_b64_e32 v[4:5], s[6:7]
	s_movk_i32 s6, 0x88
	s_movk_i32 s15, 0xb00
	v_mov_b32_e32 v2, s16
	s_mov_b32 s7, 22
	s_add_i32 s16, 0, 0x20018
	ds_write_b64 v2, v[4:5]
	v_mov_b32_e32 v6, s16
	v_mov_b64_e32 v[2:3], s[6:7]
	v_mov_b64_e32 v[4:5], s[14:15]
	s_add_i32 s6, 0, 0x20028
	ds_write2_b64 v6, v[2:3], v[4:5] offset1:1
	v_mov_b32_e32 v2, 1
	v_mov_b32_e32 v3, 16
	v_mov_b32_e32 v4, s6
	ds_write_b64 v4, v[2:3]

.LBB0_162:
	v_ashrrev_i32_e32 v7, 31, v14
	v_lshrrev_b32_e32 v7, 26, v7
	v_add_u32_e32 v7, v14, v7
	v_ashrrev_i32_e32 v15, 6, v7
	v_bfe_i32 v7, v14, 27, 1
	v_lshlrev_b32_e32 v6, 4, v14
	v_lshrrev_b32_e32 v7, 22, v7
	v_add_u32_e32 v7, v6, v7
	v_and_b32_e32 v7, 0xfffffc00, v7
	v_sub_u32_e32 v7, v6, v7
	v_lshrrev_b32_e32 v8, 4, v7
	v_bitop3_b32 v8, v8, v7, 32 bitop3:0x6c
	v_ashrrev_i32_e32 v7, 31, v7
	v_lshrrev_b32_e32 v7, 26, v7
	v_add_u32_e32 v7, v8, v7
	v_ashrrev_i32_e32 v16, 6, v7
	v_lshlrev_b32_e32 v9, 3, v15
	v_mul_i32_i24_e32 v10, 64, v16
	v_and_b32_e32 v9, -16, v9
	v_sub_u32_e32 v8, v8, v10
	v_mov_b32_e32 v10, 1
	v_add_u32_e32 v7, v16, v9
	v_lshlrev_b32_e32 v9, 5, v15
	v_ashrrev_i16_sdwa v8, v10, sext(v8) dst_sel:DWORD dst_unused:UNUSED_PAD src0_sel:DWORD src1_sel:BYTE_0
	v_and_b32_e32 v9, 32, v9
	v_bfe_i32 v17, v8, 0, 16
	v_and_b32_e32 v12, 3, v16
	s_mov_b32 s5, 0x1fffe0
	v_add_lshl_u32 v9, v9, v17, 1
	v_add_u32_e32 v6, 0x2000, v6
	v_lshlrev_b32_e32 v8, 1, v7
	v_lshrrev_b32_e32 v11, 2, v7
	v_and_or_b32 v12, v7, s5, v12
	v_lshl_add_u32 v130, v7, 11, v9
	v_ashrrev_i32_e32 v7, 31, v6
	v_lshrrev_b32_e32 v7, 22, v7
	v_add_u32_e32 v7, v6, v7
	v_ashrrev_i32_e32 v18, 10, v7
	v_mul_i32_i24_e32 v7, 0x400, v18
	v_sub_u32_e32 v6, v6, v7
	v_and_b32_e32 v8, 24, v8
	v_and_b32_e32 v11, 4, v11
	v_lshrrev_b32_e32 v7, 4, v6
	v_or3_b32 v8, v12, v11, v8
	v_bitop3_b32 v6, v7, v6, 32 bitop3:0x6c
	v_lshl_add_u32 v132, v8, 11, v9
	v_ashrrev_i32_e32 v8, 31, v6
	v_lshrrev_b32_e32 v8, 26, v8
	v_add_u32_e32 v8, v6, v8
	v_lshlrev_b32_e32 v7, 3, v18
	v_ashrrev_i32_e32 v19, 6, v8
	v_and_b32_e32 v8, 0xc0, v8
	v_and_b32_e32 v7, -16, v7
	v_sub_u32_e32 v6, v6, v8
	s_ashr_i32 s4, s16, 6
	v_add_u32_e32 v7, v19, v7
	v_ashrrev_i16_sdwa v6, v10, sext(v6) dst_sel:DWORD dst_unused:UNUSED_PAD src0_sel:DWORD src1_sel:BYTE_0
	v_lshlrev_b32_e32 v9, 5, v18
	v_bfe_i32 v20, v6, 0, 16
	v_lshlrev_b32_e32 v6, 1, v7
	v_lshrrev_b32_e32 v8, 2, v7
	v_and_b32_e32 v10, 3, v19
	s_lshl_b32 s47, s4, 10
	v_and_b32_e32 v9, 32, v9
	v_and_b32_e32 v6, 24, v6
	v_and_b32_e32 v8, 4, v8
	v_and_or_b32 v10, v7, s5, v10
	s_add_i32 s57, s47, 0
	v_or3_b32 v6, v10, v8, v6
	v_add_lshl_u32 v8, v9, v20, 1
	s_add_i32 m0, s57, 0x10000
	v_readfirstlane_b32 s14, v4
	v_readfirstlane_b32 s15, v5
	v_lshl_add_u32 v136, v6, 11, v8
	v_lshl_add_u32 v134, v7, 11, v8
	s_add_i32 s62, s57, 0x2000
	s_add_i32 s63, s57, 0x4000
	s_add_i32 s64, s57, 0x6000
	s_and_saveexec_b64 s[96:97], s[26:27]
	s_cbranch_execz .Lmy_w_1
	v_mov_b32_e32 v238, 0x257f0
	ds_read2_b32 v[234:235], v238 offset1:1
	v_add_u32_e32 v239, 1, v239
	s_add_u32 s98, s38, 0x1d6c5400
	s_addc_u32 s99, s39, 0
	s_mov_b32 s94, 0
	s_waitcnt vmcnt(0) lgkmcnt(0)
	v_mul_u32_u24_e32 v238, v239, v234
	v_add_u32_e32 v236, 1, v236
	v_mul_u32_u24_e32 v237, v239, v235
	v_cmp_eq_u32_e32 vcc, v236, v238
	v_mov_b32_e32 v238, 0
	s_cbranch_vccz .Lmy_ws_1
	buffer_wbl2 sc1
	s_waitcnt vmcnt(0)
	v_mov_b32_e32 v234, 0x1d6c5000
	v_mov_b32_e32 v235, 1
	global_atomic_add v234, v235, s[38:39] offset:1024
.Lmy_ws_1:
	global_load_dword v236, v238, s[98:99] sc1
	s_waitcnt vmcnt(0)
	v_sub_u32_e32 v236, v236, v237
	v_cmp_gt_i32_e32 vcc, 0, v236
	s_cbranch_vccz .Lmy_wd_1
	s_sleep 1
	s_add_i32 s94, s94, 1
	s_cmp_lt_u32 s94, 0x4000
	s_cbranch_scc1 .Lmy_ws_1

.LBB0_233:
	s_cmp_gt_i32 s41, 3
	s_cselect_b64 s[4:5], -1, 0
	s_and_b64 s[6:7], s[8:9], s[4:5]
	s_andn2_b64 vcc, exec, s[6:7]
	s_cbranch_vccnz .LBB0_283
	s_waitcnt vmcnt(0)
	s_waitcnt vmcnt(0) lgkmcnt(0)
	s_barrier
	s_and_saveexec_b64 s[6:7], s[26:27]
	s_cbranch_execz .Lmy_aa_2
	s_lshl_b32 s8, s3, 8
	s_add_u32 s8, s34, s8
	s_addc_u32 s9, s35, 0
	v_mov_b32_e32 v237, 0x1000
	v_mov_b32_e32 v236, 1
	global_atomic_add v236, v237, v236, s[8:9] offset:1024 sc0
.Lmy_aa_2:
	s_or_b64 exec, exec, s[6:7]
.LBB0_283:
	s_cmp_lt_i32 s40, 4
	s_cselect_b64 s[6:7], -1, 0
	s_and_b64 s[14:15], s[6:7], s[4:5]
	s_andn2_b64 vcc, exec, s[14:15]
	s_cbranch_vccnz .LBB0_372
	s_abs_i32 s22, s42
	v_cvt_f32_u32_e32 v2, s22
	s_sub_i32 s24, 0, s22
	s_mov_b32 s5, 0
	s_ashr_i32 s23, s42, 31
	v_rcp_iflag_f32_e32 v2, v2
	s_nop 0
	v_mul_f32_e32 v3, 0x4f7ffffe, v2
	v_cvt_u32_f32_e32 v3, v3
	s_nop 0
	v_readfirstlane_b32 s4, v3
	s_mul_i32 s6, s24, s4
	s_mul_hi_u32 s6, s4, s6
	s_add_i32 s4, s4, s6
	s_lshl_b64 s[6:7], s[4:5], 9
	s_and_saveexec_b64 s[8:9], s[26:27]
	s_cbranch_execz .LBB0_286
	s_add_u32 s4, s38, 0x147c2000
	s_addc_u32 s6, s39, 0
	s_add_u32 s16, s38, 0x2c00000
	s_addc_u32 s17, s39, 0
	s_add_u32 s20, s38, 0x97c2000
	s_addc_u32 s21, s39, 0
	s_add_u32 s18, s38, 0x152c2000
	s_addc_u32 s19, s39, 0
	v_mov_b32_e32 v4, s20
	s_add_i32 s20, 0, 0x20000
	v_mov_b32_e32 v5, s21
	v_mov_b32_e32 v6, s16
	v_mov_b32_e32 v7, s17
	v_mov_b32_e32 v3, s20
	s_mov_b32 s16, 0
	ds_write_b128 v3, v[4:7]
	s_add_i32 s20, 0, 0x20010
	v_mov_b64_e32 v[4:5], s[18:19]
	s_movk_i32 s18, 0x80
	s_movk_i32 s17, 0x400
	v_mov_b32_e32 v3, s20
	s_mov_b32 s19, 4
	s_add_i32 s20, 0, 0x20018
	ds_write_b64 v3, v[4:5]
	v_mov_b32_e32 v3, s20
	v_mov_b64_e32 v[4:5], s[18:19]
	v_mov_b64_e32 v[8:9], s[16:17]
	s_add_i32 s18, 0, 0x20028
	ds_write2_b64 v3, v[4:5], v[8:9] offset1:1
	v_mov_b32_e32 v4, 4
	v_mov_b32_e32 v5, 44
	v_mov_b32_e32 v3, s18
	ds_write_b64 v3, v[4:5]
	v_mov_b32_e32 v4, s4
	s_add_i32 s4, 0, 0x20030
	v_mov_b32_e32 v5, s6
	v_mov_b32_e32 v3, s4
	s_add_i32 s4, 0, 0x20040
	ds_write_b128 v3, v[4:7]
	v_mov_b32_e32 v3, s4
	v_mov_b64_e32 v[4:5], s[36:37]
	s_movk_i32 s28, 0x200
	s_mov_b32 s29, s17
	s_add_i32 s4, 0, 0x20048
	ds_write_b64 v3, v[4:5]
	v_mov_b32_e32 v3, s4
	v_mov_b64_e32 v[6:7], s[28:29]
	s_mov_b32 s29, 12
	s_mov_b32 s28, s16
	s_add_i32 s4, 0, 0x20058
	s_mov_b32 s20, 8
	s_mov_b32 s21, s19
	v_mov_b64_e32 v[8:9], s[28:29]
	s_add_u32 s28, s36, 0x400000
	v_mov_b64_e32 v[4:5], s[20:21]
	s_addc_u32 s29, s37, 0
	ds_write2_b64 v3, v[4:5], v[6:7] offset1:1
	v_mov_b32_e32 v3, s4
	s_add_u32 s4, s38, 0x2c00600
	s_addc_u32 s6, s39, 0
	s_add_u32 s18, s38, 0x147c2600
	s_addc_u32 s21, s39, 0
	v_mov_b32_e32 v6, s4
	s_add_i32 s4, 0, 0x20060
	ds_write_b64 v3, v[8:9]
	v_mov_b32_e32 v4, s18
	v_mov_b32_e32 v5, s21
	v_mov_b32_e32 v7, s6
	v_mov_b32_e32 v3, s4
	s_add_i32 s4, 0, 0x20070
	ds_write_b128 v3, v[4:7]
	v_mov_b32_e32 v3, s4
	v_mov_b64_e32 v[4:5], s[28:29]
	s_add_i32 s4, 0, 0x20078
	ds_write_b64 v3, v[4:5]
	s_movk_i32 s28, 0x220
	s_mov_b32 s29, s17
	v_mov_b32_e32 v3, s4
	s_add_i32 s4, 0, 0x20088
	s_mov_b32 s21, s19
	v_mov_b64_e32 v[6:7], s[28:29]
	s_add_u32 s28, s36, 0x800000
	v_mov_b64_e32 v[4:5], s[20:21]
	s_addc_u32 s29, s37, 0
	ds_write2_b64 v3, v[4:5], v[6:7] offset1:1
	v_mov_b32_e32 v3, s4
	s_add_u32 s4, s38, 0x2c00c00
	s_addc_u32 s6, s39, 0
	s_add_u32 s18, s38, 0x147c2c00
	s_addc_u32 s21, s39, 0
	v_mov_b32_e32 v6, s4
	s_add_i32 s4, 0, 0x20090
	ds_write_b64 v3, v[8:9]
	v_mov_b32_e32 v4, s18
	v_mov_b32_e32 v5, s21
	v_mov_b32_e32 v7, s6
	v_mov_b32_e32 v3, s4
	s_add_i32 s4, 0, 0x200a0
	ds_write_b128 v3, v[4:7]
	v_mov_b32_e32 v3, s4
	v_mov_b64_e32 v[4:5], s[28:29]
	s_movk_i32 s28, 0x240
	s_mov_b32 s29, s17
	s_add_i32 s4, 0, 0x200a8
	ds_write_b64 v3, v[4:5]
	v_mov_b32_e32 v3, s4
	v_mov_b64_e32 v[6:7], s[28:29]
	s_mov_b32 s29, 10
	s_mov_b32 s28, s16
	s_add_i32 s4, 0, 0x200b8
	s_mov_b32 s21, s19
	v_mov_b64_e32 v[8:9], s[28:29]
	s_add_u32 s28, s36, 0xc00000
	v_mov_b64_e32 v[4:5], s[20:21]
	s_addc_u32 s29, s37, 0
	ds_write2_b64 v3, v[4:5], v[6:7] offset1:1
	v_mov_b32_e32 v3, s4
	s_add_u32 s4, s38, 0x2c01100
	s_addc_u32 s6, s39, 0
	s_add_u32 s16, s38, 0x147c3100
	s_addc_u32 s18, s39, 0
	v_mov_b32_e32 v6, s4
	s_add_i32 s4, 0, 0x200c0
	ds_write_b64 v3, v[8:9]
	v_mov_b32_e32 v4, s16
	v_mov_b32_e32 v5, s18
	v_mov_b32_e32 v7, s6
	v_mov_b32_e32 v3, s4
	s_add_i32 s4, 0, 0x200d0
	ds_write_b128 v3, v[4:7]
	v_mov_b32_e32 v3, s4
	v_mov_b64_e32 v[4:5], s[28:29]
	s_movk_i32 s16, 0x260
	s_add_i32 s4, 0, 0x200d8
	ds_write_b64 v3, v[4:5]
	v_mov_b32_e32 v3, s4
	v_mov_b64_e32 v[4:5], s[20:21]
	v_mov_b64_e32 v[6:7], s[16:17]
	s_add_i32 s4, 0, 0x200e8
	ds_write2_b64 v3, v[4:5], v[6:7] offset1:1
	v_mov_b32_e32 v3, s4
	ds_write_b64 v3, v[8:9]
.LBB0_286:
	s_or_b64 exec, exec, s[8:9]
	s_mul_i32 s4, s7, s22
	s_sub_i32 s4, 0x200, s4
	s_add_i32 s6, s7, 1
	s_sub_i32 s9, s4, s22
	s_cmp_ge_u32 s4, s22
	s_cselect_b32 s6, s6, s7
	s_cselect_b32 s4, s9, s4
	s_add_i32 s7, s6, 1
	s_cmp_ge_u32 s4, s22
	s_cselect_b32 s4, s7, s6
	s_xor_b32 s4, s4, s23
	s_sub_i32 s45, s4, s23
	s_mul_i32 s4, s45, s42
	s_cmpk_eq_i32 s4, 0x200
	s_cselect_b64 s[6:7], -1, 0
	v_mov_b32_e32 v12, v1
	s_movk_i32 s8, 0x200
	s_waitcnt lgkmcnt(0)
	s_barrier
	s_movk_i32 s17, 0x280
	v_readfirstlane_b32 s4, v12
	s_and_b64 vcc, exec, s[6:7]
	s_mov_b32 s16, 0
	s_mov_b32 s9, 0
	s_cbranch_vccz .LBB0_290
	v_mul_f32_e32 v2, 0x4f7ffffe, v2
	v_cvt_u32_f32_e32 v2, v2
	s_nop 0
	v_readfirstlane_b32 s5, v2
	s_mul_i32 s24, s24, s5
	s_mul_hi_u32 s16, s5, s24
	s_add_i32 s5, s5, s16
	s_lshr_b32 s5, s5, 23
	s_mul_i32 s16, s5, s22
	s_sub_i32 s16, 0x200, s16
	s_add_i32 s17, s5, 1
	s_sub_i32 s18, s16, s22
	s_cmp_ge_u32 s16, s22
	s_cselect_b32 s5, s17, s5
	s_cselect_b32 s16, s18, s16
	s_add_i32 s17, s5, 1
	s_cmp_ge_u32 s16, s22
	s_cselect_b32 s5, s17, s5
	s_xor_b32 s5, s5, s23
	s_sub_i32 s17, s5, s23
	s_cmp_gt_i32 s17, 0
	s_mov_b32 s16, 0
	s_mov_b32 s5, 0
	s_cbranch_scc1 .LBB0_289
	s_sub_i32 s9, 0, s17
	s_mov_b32 s5, 1
	s_movk_i32 s8, 0x80
	s_movk_i32 s16, 0x200

.LBB0_295:
	v_ashrrev_i32_e32 v5, 31, v12
	v_lshrrev_b32_e32 v5, 26, v5
	v_add_u32_e32 v5, v12, v5
	v_ashrrev_i32_e32 v13, 6, v5
	v_bfe_i32 v5, v12, 27, 1
	v_lshlrev_b32_e32 v4, 4, v12
	v_lshrrev_b32_e32 v5, 22, v5
	v_add_u32_e32 v5, v4, v5
	v_and_b32_e32 v5, 0xfffffc00, v5
	v_sub_u32_e32 v5, v4, v5
	v_lshrrev_b32_e32 v6, 4, v5
	v_bitop3_b32 v6, v6, v5, 32 bitop3:0x6c
	v_ashrrev_i32_e32 v5, 31, v5
	v_lshrrev_b32_e32 v5, 26, v5
	v_lshlrev_b32_e32 v7, 3, v13
	v_add_u32_e32 v5, v6, v5
	v_and_b32_e32 v7, -16, v7
	v_ashrrev_i32_e32 v14, 6, v5
	v_add_u32_e32 v5, v14, v7
	v_lshlrev_b32_e32 v7, 5, v13
	v_and_b32_e32 v15, 32, v7
	v_mul_i32_i24_e32 v7, 64, v14
	v_sub_u32_e32 v6, v6, v7
	v_mov_b32_e32 v7, 1
	v_ashrrev_i16_sdwa v6, v7, sext(v6) dst_sel:DWORD dst_unused:UNUSED_PAD src0_sel:DWORD src1_sel:BYTE_0
	v_lshlrev_b32_e32 v8, 1, v5
	v_lshrrev_b32_e32 v9, 2, v5
	v_and_b32_e32 v10, 3, v14
	s_mov_b32 s9, 0xffffe0
	v_bfe_i32 v16, v6, 0, 16
	v_and_b32_e32 v8, 24, v8
	v_and_b32_e32 v9, 4, v9
	v_and_or_b32 v10, v5, s9, v10
	s_movk_i32 s8, 0xb00
	v_add_u32_e32 v6, v15, v16
	v_or3_b32 v8, v10, v9, v8
	v_mul_lo_u32 v5, v5, s8
	v_add_lshl_u32 v130, v6, v5, 1
	v_mul_u32_u24_e32 v5, 0xb00, v8
	v_add_u32_e32 v4, 0x2000, v4
	v_add_lshl_u32 v132, v5, v6, 1
	v_ashrrev_i32_e32 v5, 31, v4
	v_lshrrev_b32_e32 v5, 22, v5
	v_add_u32_e32 v5, v4, v5
	v_ashrrev_i32_e32 v17, 10, v5
	v_mul_i32_i24_e32 v5, 0x400, v17
	v_sub_u32_e32 v4, v4, v5
	v_lshrrev_b32_e32 v5, 4, v4
	v_bitop3_b32 v4, v5, v4, 32 bitop3:0x6c
	v_ashrrev_i32_e32 v6, 31, v4
	v_lshrrev_b32_e32 v6, 26, v6
	v_lshlrev_b32_e32 v5, 3, v17
	v_add_u32_e32 v6, v4, v6
	v_and_b32_e32 v5, -16, v5
	v_ashrrev_i32_e32 v19, 6, v6
	v_and_b32_e32 v6, 0xc0, v6
	v_add_u32_e32 v5, v19, v5
	v_lshlrev_b32_e32 v8, 5, v17
	v_sub_u32_e32 v4, v4, v6
	s_ashr_i32 s5, s4, 6
	v_and_b32_e32 v18, 32, v8
	v_ashrrev_i16_sdwa v4, v7, sext(v4) dst_sel:DWORD dst_unused:UNUSED_PAD src0_sel:DWORD src1_sel:BYTE_0
	v_lshlrev_b32_e32 v6, 1, v5
	v_lshrrev_b32_e32 v7, 2, v5
	v_and_b32_e32 v8, 3, v19
	v_bfe_i32 v20, v4, 0, 16
	v_and_b32_e32 v6, 24, v6
	v_and_b32_e32 v7, 4, v7
	v_and_or_b32 v8, v5, s9, v8
	s_lshl_b32 s54, s5, 10
	v_add_u32_e32 v4, v18, v20
	v_or3_b32 v6, v8, v7, v6
	v_mul_lo_u32 v5, v5, s8
	s_add_i32 s55, s54, 0
	v_add_lshl_u32 v134, v4, v5, 1
	v_mul_u32_u24_e32 v5, 0xb00, v6
	s_add_i32 m0, s55, 0x10000
	v_readfirstlane_b32 s16, v2
	v_readfirstlane_b32 s17, v3
	v_add_lshl_u32 v136, v5, v4, 1
	s_add_i32 s56, s55, 0x2000
	s_add_i32 s57, s55, 0x4000
	s_add_i32 s58, s55, 0x6000
	s_ashr_i32 s9, s4, 8
	s_and_saveexec_b64 s[96:97], s[26:27]
	s_cbranch_execz .Lmy_w_2
	v_mov_b32_e32 v238, 0x257f0
	ds_read2_b32 v[234:235], v238 offset1:1
	v_add_u32_e32 v239, 1, v239
	s_add_u32 s98, s38, 0x1d6c5400
	s_addc_u32 s99, s39, 0
	s_mov_b32 s94, 0
	s_waitcnt vmcnt(0) lgkmcnt(0)
	v_mul_u32_u24_e32 v238, v239, v234
	v_add_u32_e32 v236, 1, v236
	v_mul_u32_u24_e32 v237, v239, v235
	v_cmp_eq_u32_e32 vcc, v236, v238
	v_mov_b32_e32 v238, 0
	s_cbranch_vccz .Lmy_ws_2
	buffer_wbl2 sc1
	s_waitcnt vmcnt(0)
	v_mov_b32_e32 v234, 0x1d6c5000
	v_mov_b32_e32 v235, 1
	global_atomic_add v234, v235, s[38:39] offset:1024

.LBB0_372:
	s_cmp_gt_i32 s41, 4
	s_cselect_b64 s[4:5], -1, 0
	s_and_b64 s[6:7], s[14:15], s[4:5]
	s_andn2_b64 vcc, exec, s[6:7]
	s_cbranch_vccnz .LBB0_422
	s_waitcnt vmcnt(0)
	s_waitcnt vmcnt(0) lgkmcnt(0)
	s_barrier
	s_and_saveexec_b64 s[6:7], s[26:27]
	s_cbranch_execz .LBB0_421
	v_add_u32_e32 v239, 1, v239
	s_add_i32 s8, 0, 0x257f0
	v_mov_b32_e32 v2, s8
	s_waitcnt vmcnt(0) expcnt(0) lgkmcnt(0)
	ds_read_b32 v4, v2
	s_add_i32 s8, 0, 0x257f4
	v_mov_b32_e32 v2, s8
	ds_read_b32 v2, v2
	s_waitcnt lgkmcnt(1)
	v_cmp_ne_u32_e32 vcc, 0, v4
	s_cbranch_vccnz .LBB0_389
	s_add_u32 s8, s38, 0x1d6c2200
	s_addc_u32 s9, s39, 0
	s_add_u32 s14, s38, 0x1d6c2400
	s_addc_u32 s15, s39, 0
	s_add_u32 s16, s38, 0x1d6c2500
	s_addc_u32 s17, s39, 0
	s_add_u32 s18, s38, 0x1d6c2600
	s_addc_u32 s19, s39, 0
	s_add_u32 s20, s38, 0x1d6c2700
	s_addc_u32 s21, s39, 0
	s_add_u32 s22, s38, 0x1d6c2800
	s_addc_u32 s23, s39, 0
	s_add_u32 s24, s38, 0x1d6c2900
	s_addc_u32 s25, s39, 0
	s_add_u32 s28, s38, 0x1d6c2a00
	s_addc_u32 s29, s39, 0
	s_add_u32 s44, s38, 0x1d6c2b00
	s_addc_u32 s45, s39, 0
	s_add_u32 s46, s38, 0x1d6c2c00
	s_addc_u32 s47, s39, 0
	s_add_u32 s48, s38, 0x1d6c2d00
	s_addc_u32 s49, s39, 0
	s_add_u32 s50, s38, 0x1d6c2e00
	s_addc_u32 s51, s39, 0
	s_add_u32 s54, s38, 0x1d6c2f00
	s_addc_u32 s55, s39, 0
	s_add_u32 s56, s38, 0x1d6c3000
	s_addc_u32 s57, s39, 0
	s_add_u32 s58, s38, 0x1d6c3100
	s_addc_u32 s59, s39, 0
	s_add_u32 s60, s38, 0x1d6c3200
	s_addc_u32 s61, s39, 0
	s_mul_i32 s72, s43, s33
	s_add_u32 s62, s38, 0x1d6c3300
	s_mul_i32 s72, s72, s42
	s_addc_u32 s63, s39, 0
	s_mov_b32 s73, 1
	v_mov_b32_e32 v18, 0
	s_branch .LBB0_377

.LBB0_434:
	s_cmp_gt_i32 s41, 5
	s_cselect_b64 s[4:5], -1, 0
	s_and_b64 s[6:7], s[8:9], s[4:5]
	s_andn2_b64 vcc, exec, s[6:7]
	s_cbranch_vccnz .LBB0_484
	s_waitcnt vmcnt(0)
	s_waitcnt vmcnt(0) lgkmcnt(0)
	s_barrier
	s_and_saveexec_b64 s[6:7], s[26:27]
	s_cbranch_execz .Lmy_aa_4
	s_lshl_b32 s8, s3, 8
	s_add_u32 s8, s34, s8
	s_addc_u32 s9, s35, 0
	v_mov_b32_e32 v237, 0x1000
	v_mov_b32_e32 v236, 1
	global_atomic_add v236, v237, v236, s[8:9] offset:1024 sc0
.Lmy_aa_4:
	s_or_b64 exec, exec, s[6:7]
.LBB0_484:
	s_cmp_lt_i32 s40, 6
	s_cselect_b64 s[6:7], -1, 0
	s_and_b64 s[8:9], s[6:7], s[4:5]
	s_andn2_b64 vcc, exec, s[8:9]
	s_cbranch_vccnz .LBB0_561
	s_waitcnt lgkmcnt(0)
	s_and_saveexec_b64 s[10:11], s[26:27]
	s_cbranch_execz .LBB0_487
	s_add_u32 s44, s38, 0x4600000
	s_addc_u32 s45, s39, 0
	s_add_u32 s12, s38, 0xf9c2000
	s_addc_u32 s13, s39, 0
	s_add_u32 s16, s38, 0xf7c2000
	s_addc_u32 s17, s39, 0
	s_add_u32 s46, s38, 0x93c2000
	s_addc_u32 s47, s39, 0
	s_add_u32 s48, s38, 0x4500000
	s_addc_u32 s49, s39, 0
	s_add_u32 s20, s38, 0xd7c2000
	s_addc_u32 s21, s39, 0
	s_add_u32 s22, s38, 0x97c2400
	s_addc_u32 s23, s39, 0
	s_add_u32 s50, s38, 0x4400000
	s_addc_u32 s51, s39, 0
	s_add_u32 s6, s38, 0x4200000
	s_addc_u32 s7, s39, 0
	s_add_u32 s18, s38, 0x97c2000
	s_addc_u32 s19, s39, 0
	s_add_u32 s4, s38, 0x53c2000
	s_addc_u32 s5, s39, 0
	s_add_i32 s24, 0, 0x20000
	v_mov_b64_e32 v[4:5], s[4:5]
	s_mov_b32 s14, 0
	v_mov_b32_e32 v2, s24
	v_mov_b64_e32 v[6:7], s[6:7]
	s_add_i32 s6, 0, 0x20010
	s_movk_i32 s24, 0x80
	s_movk_i32 s15, 0x400
	ds_write_b128 v2, v[4:7]
	v_mov_b32_e32 v2, s6
	v_mov_b64_e32 v[4:5], s[18:19]
	s_mov_b32 s25, 4
	s_add_i32 s6, 0, 0x20018
	ds_write_b64 v2, v[4:5]
	v_mov_b32_e32 v6, s6
	v_mov_b64_e32 v[2:3], s[24:25]
	v_mov_b64_e32 v[4:5], s[14:15]
	s_add_i32 s6, 0, 0x20028
	ds_write2_b64 v6, v[2:3], v[4:5] offset1:1
	v_mov_b32_e32 v2, s6
	s_mov_b32 s6, s50
	s_mov_b32 s7, s51
	v_mov_b32_e32 v6, 2
	v_mov_b32_e32 v7, 16
	s_add_i32 s18, 0, 0x20030
	v_mov_b64_e32 v[10:11], s[6:7]
	ds_write_b64 v2, v[6:7]
	v_mov_b32_e32 v2, s18
	v_mov_b64_e32 v[8:9], s[4:5]
	s_add_i32 s6, 0, 0x20040
	s_mov_b32 s19, 2
	ds_write_b128 v2, v[8:11]
	v_mov_b32_e32 v2, s6
	v_mov_b64_e32 v[4:5], s[22:23]
	s_movk_i32 s6, 0x200
	s_mov_b32 s18, s24
	s_mov_b32 s7, s15
	s_add_i32 s22, 0, 0x20048
	ds_write_b64 v2, v[4:5]
	v_mov_b32_e32 v6, s22
	v_mov_b64_e32 v[2:3], s[18:19]
	v_mov_b64_e32 v[4:5], s[6:7]
	s_add_i32 s6, 0, 0x20058
	ds_write2_b64 v6, v[2:3], v[4:5] offset1:1
	v_mov_b32_e32 v2, s6
	s_mov_b32 s6, s48
	s_mov_b32 s7, s49
	v_mov_b32_e32 v6, 0
	s_add_i32 s18, 0, 0x20060
	v_mov_b64_e32 v[10:11], s[6:7]
	ds_write_b64 v2, v[6:7]
	v_mov_b32_e32 v2, s18
	v_mov_b64_e32 v[8:9], s[4:5]
	s_add_i32 s6, 0, 0x20070
	ds_write_b128 v2, v[8:11]
	v_mov_b32_e32 v2, s6
	s_movk_i32 s6, 0x300
	s_mov_b32 s28, 5
	v_mov_b64_e32 v[4:5], s[20:21]
	s_mov_b32 s7, 12
	s_mov_b32 s18, s24
	s_add_i32 s20, 0, 0x20078
	s_mov_b32 s29, 16
	ds_write_b64 v2, v[4:5]
	v_mov_b32_e32 v6, s20
	v_mov_b64_e32 v[2:3], s[18:19]
	v_mov_b64_e32 v[4:5], s[6:7]
	s_add_i32 s6, 0, 0x20088
	ds_write2_b64 v6, v[2:3], v[4:5] offset1:1
	v_mov_b32_e32 v2, s6
	v_mov_b64_e32 v[8:9], s[28:29]
	s_add_i32 s6, 0, 0x20090
	ds_write_b64 v2, v[8:9]
	v_mov_b32_e32 v2, s46
	v_mov_b32_e32 v3, s47
	v_mov_b32_e32 v4, s48
	v_mov_b32_e32 v5, s49
	v_mov_b32_e32 v6, s6
	s_add_i32 s6, 0, 0x200a0
	s_mov_b32 s18, 8
	ds_write_b128 v6, v[2:5]
	v_mov_b32_e32 v2, s6
	v_mov_b64_e32 v[4:5], s[16:17]
	s_mov_b32 s6, s15
	s_mov_b32 s7, s18
	s_add_i32 s15, 0, 0x200a8
	ds_write_b64 v2, v[4:5]
	v_mov_b32_e32 v6, s15
	v_mov_b64_e32 v[2:3], s[18:19]
	v_mov_b64_e32 v[4:5], s[6:7]
	s_add_i32 s6, 0, 0x200b8
	ds_write2_b64 v6, v[2:3], v[4:5] offset1:1
	v_mov_b32_e32 v2, s6
	v_mov_b32_e32 v4, s4
	s_add_i32 s4, 0, 0x200c0
	ds_write_b64 v2, v[8:9]
	v_mov_b32_e32 v2, s44
	v_mov_b32_e32 v3, s45
	v_mov_b32_e32 v5, s5
	v_mov_b32_e32 v6, s4
	s_add_i32 s4, 0, 0x200d0
	ds_write_b128 v6, v[2:5]
	v_mov_b32_e32 v2, s4
	v_mov_b64_e32 v[4:5], s[12:13]
	s_movk_i32 s4, 0x410
	s_movk_i32 s7, 0x88
	s_mov_b32 s6, s19
	s_mov_b32 s5, s14
	s_add_i32 s12, 0, 0x200d8
	ds_write_b64 v2, v[4:5]
	v_mov_b32_e32 v6, s12
	v_mov_b64_e32 v[2:3], s[6:7]
	v_mov_b64_e32 v[4:5], s[4:5]
	s_add_i32 s4, 0, 0x200e8
	ds_write2_b64 v6, v[2:3], v[4:5] offset1:1
	v_mov_b32_e32 v6, 6
	v_mov_b32_e32 v2, s4
	ds_write_b64 v2, v[6:7]
.LBB0_487:
	s_or_b64 exec, exec, s[10:11]
	s_cmpk_lt_i32 s2, 0x520
	v_mov_b32_e32 v14, v1
	s_cselect_b64 s[4:5], -1, 0
	s_cmpk_gt_i32 s2, 0x51f
	s_waitcnt lgkmcnt(0)
	s_barrier
	s_nop 0
	v_readfirstlane_b32 s18, v14
	s_cbranch_scc1 .LBB0_489
	s_ashr_i32 s6, s2, 31
	s_lshr_b32 s6, s6, 29
	s_add_i32 s6, s2, s6
	s_ashr_i32 s7, s6, 3
	s_and_b32 s6, s6, -8
	s_sub_i32 s6, s2, s6
	s_cmp_lt_i32 s6, 0
	s_movk_i32 s10, 0xa5
	s_cselect_b32 s10, s10, 0xa4
	s_mul_i32 s6, s6, s10
	s_add_i32 s6, s6, s7
	s_add_i32 s7, 0, 0x20050
	v_mov_b32_e32 v2, s7
	s_add_i32 s7, 0, 0x20080
	ds_read_b32 v2, v2
	v_mov_b32_e32 v3, s7
	s_add_i32 s7, 0, 0x200b0
	v_mov_b32_e32 v4, s7
	s_add_i32 s7, 0, 0x200e0
	v_mov_b32_e32 v5, s7
	ds_read_b32 v3, v3
	ds_read_b32 v4, v4
	ds_read_b32 v5, v5
	s_waitcnt lgkmcnt(3)
	v_cmp_ge_i32_e32 vcc, s6, v2
	s_nop 1
	v_cndmask_b32_e64 v2, 0, 1, vcc
	s_waitcnt lgkmcnt(2)
	v_cmp_lt_i32_e32 vcc, s6, v3
	s_nop 1
	v_cndmask_b32_e32 v2, 2, v2, vcc
	s_waitcnt lgkmcnt(1)
	v_cmp_lt_i32_e32 vcc, s6, v4
	s_nop 1
	v_cndmask_b32_e32 v2, 3, v2, vcc
	s_waitcnt lgkmcnt(0)
	v_cmp_lt_i32_e32 vcc, s6, v5
	s_nop 1
	v_cndmask_b32_e32 v2, 4, v2, vcc
	s_nop 0
	v_readfirstlane_b32 s50, v2
	s_mul_i32 s7, s50, 48
	s_add_i32 s7, s7, 0
	s_add_i32 s7, s7, 0x20000
	v_mov_b32_e32 v4, s7
	ds_read_b64 v[2:3], v4 offset:24
	ds_read2_b32 v[140:141], v4 offset0:8 offset1:11
	s_waitcnt lgkmcnt(1)
	v_readfirstlane_b32 s7, v3
	s_lshl_b32 s7, s7, 3
	s_abs_i32 s10, s7
	v_cvt_f32_u32_e32 v3, s10
	v_readfirstlane_b32 s11, v2
	s_sub_i32 s14, 0, s10
	s_waitcnt lgkmcnt(0)
	v_readfirstlane_b32 s12, v140
	v_rcp_iflag_f32_e32 v2, v3
	s_sub_i32 s6, s6, s12
	s_abs_i32 s13, s6
	s_xor_b32 s12, s6, s7
	v_mul_f32_e32 v2, 0x4f7ffffe, v2
	v_cvt_u32_f32_e32 v2, v2
	s_ashr_i32 s12, s12, 31
	v_readfirstlane_b32 s15, v2
	s_mul_i32 s14, s14, s15
	s_mul_hi_u32 s14, s15, s14
	s_add_i32 s15, s15, s14
	s_mul_hi_u32 s14, s13, s15
	s_mul_i32 s15, s14, s10
	s_sub_i32 s13, s13, s15
	s_add_i32 s15, s14, 1
	s_sub_i32 s16, s13, s10
	s_cmp_ge_u32 s13, s10
	s_cselect_b32 s14, s15, s14
	s_cselect_b32 s13, s16, s13
	s_add_i32 s15, s14, 1
	s_cmp_ge_u32 s13, s10
	s_cselect_b32 s10, s15, s14
	s_xor_b32 s10, s10, s12
	s_sub_i32 s10, s10, s12
	s_lshl_b32 s12, s10, 3
	s_sub_i32 s11, s11, s12
	s_min_i32 s11, s11, 8
	s_abs_i32 s13, s11
	v_cvt_f32_u32_e32 v6, s13
	s_sub_i32 s14, 0, s13
	s_mul_i32 s10, s10, s7
	s_sub_i32 s6, s6, s10
	v_rcp_iflag_f32_e32 v6, v6
	s_abs_i32 s10, s6
	s_xor_b32 s7, s6, s11
	s_ashr_i32 s7, s7, 31
	v_mul_f32_e32 v6, 0x4f7ffffe, v6
	v_cvt_u32_f32_e32 v6, v6
	ds_read_b128 v[2:5], v4
	v_readfirstlane_b32 s15, v6
	s_mul_i32 s14, s14, s15
	s_mul_hi_u32 s14, s15, s14
	s_add_i32 s15, s15, s14
	s_mul_hi_u32 s14, s10, s15
	s_mul_i32 s15, s14, s13
	s_sub_i32 s10, s10, s15
	s_add_i32 s15, s14, 1
	s_sub_i32 s16, s10, s13
	s_cmp_ge_u32 s10, s13
	s_cselect_b32 s14, s15, s14
	s_cselect_b32 s10, s16, s10
	s_add_i32 s15, s14, 1
	s_cmp_ge_u32 s10, s13
	s_cselect_b32 s10, s15, s14
	s_xor_b32 s10, s10, s7
	s_sub_i32 s48, s10, s7
	s_mul_i32 s7, s48, s11
	s_sub_i32 s6, s6, s7
	s_add_i32 s6, s6, s12
	s_ashr_i32 s7, s6, 31
	s_lshl_b64 s[10:11], s[6:7], 19
	s_ashr_i32 s49, s48, 31
	s_waitcnt lgkmcnt(0)
	v_lshl_add_u64 v[2:3], v[2:3], 0, s[10:11]
	s_lshl_b64 s[10:11], s[48:49], 19
	v_lshl_add_u64 v[4:5], v[4:5], 0, s[10:11]
	s_andn2_b64 vcc, exec, s[4:5]
	s_cbranch_vccz .LBB0_490
	s_branch .LBB0_561

.LBB0_490:
	v_ashrrev_i32_e32 v7, 31, v14
	v_lshrrev_b32_e32 v7, 26, v7
	v_add_u32_e32 v7, v14, v7
	v_ashrrev_i32_e32 v15, 6, v7
	v_bfe_i32 v7, v14, 27, 1
	v_lshlrev_b32_e32 v6, 4, v14
	v_lshrrev_b32_e32 v7, 22, v7
	v_add_u32_e32 v7, v6, v7
	v_and_b32_e32 v7, 0xfffffc00, v7
	v_sub_u32_e32 v7, v6, v7
	v_lshrrev_b32_e32 v8, 4, v7
	v_bitop3_b32 v8, v8, v7, 32 bitop3:0x6c
	v_ashrrev_i32_e32 v7, 31, v7
	v_lshrrev_b32_e32 v7, 26, v7
	v_add_u32_e32 v7, v8, v7
	v_ashrrev_i32_e32 v16, 6, v7
	v_lshlrev_b32_e32 v9, 3, v15
	v_mul_i32_i24_e32 v10, 64, v16
	v_and_b32_e32 v9, -16, v9
	v_sub_u32_e32 v8, v8, v10
	v_mov_b32_e32 v10, 1
	v_add_u32_e32 v7, v16, v9
	v_lshlrev_b32_e32 v9, 5, v15
	v_ashrrev_i16_sdwa v8, v10, sext(v8) dst_sel:DWORD dst_unused:UNUSED_PAD src0_sel:DWORD src1_sel:BYTE_0
	v_and_b32_e32 v9, 32, v9
	v_bfe_i32 v17, v8, 0, 16
	v_and_b32_e32 v12, 3, v16
	s_mov_b32 s5, 0x1fffe0
	v_add_lshl_u32 v9, v9, v17, 1
	v_add_u32_e32 v6, 0x2000, v6
	v_lshlrev_b32_e32 v8, 1, v7
	v_lshrrev_b32_e32 v11, 2, v7
	v_and_or_b32 v12, v7, s5, v12
	v_lshl_add_u32 v130, v7, 11, v9
	v_ashrrev_i32_e32 v7, 31, v6
	v_lshrrev_b32_e32 v7, 22, v7
	v_add_u32_e32 v7, v6, v7
	v_ashrrev_i32_e32 v18, 10, v7
	v_mul_i32_i24_e32 v7, 0x400, v18
	v_sub_u32_e32 v6, v6, v7
	v_and_b32_e32 v8, 24, v8
	v_and_b32_e32 v11, 4, v11
	v_lshrrev_b32_e32 v7, 4, v6
	v_or3_b32 v8, v12, v11, v8
	v_bitop3_b32 v6, v7, v6, 32 bitop3:0x6c
	v_lshl_add_u32 v132, v8, 11, v9
	v_ashrrev_i32_e32 v8, 31, v6
	v_lshrrev_b32_e32 v8, 26, v8
	v_add_u32_e32 v8, v6, v8
	v_lshlrev_b32_e32 v7, 3, v18
	v_ashrrev_i32_e32 v19, 6, v8
	v_and_b32_e32 v8, 0xc0, v8
	v_and_b32_e32 v7, -16, v7
	v_sub_u32_e32 v6, v6, v8
	s_ashr_i32 s4, s18, 6
	v_add_u32_e32 v7, v19, v7
	v_ashrrev_i16_sdwa v6, v10, sext(v6) dst_sel:DWORD dst_unused:UNUSED_PAD src0_sel:DWORD src1_sel:BYTE_0
	v_lshlrev_b32_e32 v9, 5, v18
	v_bfe_i32 v20, v6, 0, 16
	v_lshlrev_b32_e32 v6, 1, v7
	v_lshrrev_b32_e32 v8, 2, v7
	v_and_b32_e32 v10, 3, v19
	s_lshl_b32 s25, s4, 10
	v_and_b32_e32 v9, 32, v9
	v_and_b32_e32 v6, 24, v6
	v_and_b32_e32 v8, 4, v8
	v_and_or_b32 v10, v7, s5, v10
	s_add_i32 s49, s25, 0
	v_or3_b32 v6, v10, v8, v6
	v_add_lshl_u32 v8, v9, v20, 1
	s_add_i32 m0, s49, 0x10000
	v_readfirstlane_b32 s10, v4
	v_readfirstlane_b32 s11, v5
	v_lshl_add_u32 v136, v6, 11, v8
	v_lshl_add_u32 v134, v7, 11, v8
	s_add_i32 s58, s49, 0x2000
	s_add_i32 s59, s49, 0x4000
	s_add_i32 s60, s49, 0x6000
	s_and_saveexec_b64 s[96:97], s[26:27]
	s_cbranch_execz .Lmy_w_4
	v_mov_b32_e32 v238, 0x257f0
	ds_read2_b32 v[234:235], v238 offset1:1
	v_add_u32_e32 v239, 1, v239
	s_add_u32 s98, s38, 0x1d6c5400
	s_addc_u32 s99, s39, 0
	s_mov_b32 s94, 0
	s_waitcnt vmcnt(0) lgkmcnt(0)
	v_mul_u32_u24_e32 v238, v239, v234
	v_add_u32_e32 v236, 1, v236
	v_mul_u32_u24_e32 v237, v239, v235
	v_cmp_eq_u32_e32 vcc, v236, v238
	v_mov_b32_e32 v238, 0
	s_cbranch_vccz .Lmy_ws_4
	buffer_wbl2 sc1
	s_waitcnt vmcnt(0)
	v_mov_b32_e32 v234, 0x1d6c5000
	v_mov_b32_e32 v235, 1
	global_atomic_add v234, v235, s[38:39] offset:1024

.LBB0_561:
	s_cmp_gt_i32 s41, 6
	s_cselect_b64 s[4:5], -1, 0
	s_and_b64 s[6:7], s[8:9], s[4:5]
	s_andn2_b64 vcc, exec, s[6:7]
	s_cbranch_vccnz .LBB0_611
	s_waitcnt vmcnt(0)
	s_waitcnt vmcnt(0) lgkmcnt(0)
	s_barrier
	s_and_saveexec_b64 s[6:7], s[26:27]
	s_cbranch_execz .LBB0_610
	v_add_u32_e32 v239, 1, v239
	s_add_i32 s8, 0, 0x257f0
	v_mov_b32_e32 v2, s8
	s_waitcnt vmcnt(0) expcnt(0) lgkmcnt(0)
	ds_read_b32 v4, v2
	s_add_i32 s8, 0, 0x257f4
	v_mov_b32_e32 v2, s8
	ds_read_b32 v2, v2
	s_waitcnt lgkmcnt(1)
	v_cmp_ne_u32_e32 vcc, 0, v4
	s_cbranch_vccnz .LBB0_578
	s_add_u32 s8, s38, 0x1d6c2200
	s_addc_u32 s9, s39, 0
	s_add_u32 s10, s38, 0x1d6c2400
	s_addc_u32 s11, s39, 0
	s_add_u32 s12, s38, 0x1d6c2500
	s_addc_u32 s13, s39, 0
	s_add_u32 s14, s38, 0x1d6c2600
	s_addc_u32 s15, s39, 0
	s_add_u32 s16, s38, 0x1d6c2700
	s_addc_u32 s17, s39, 0
	s_add_u32 s18, s38, 0x1d6c2800
	s_addc_u32 s19, s39, 0
	s_add_u32 s20, s38, 0x1d6c2900
	s_addc_u32 s21, s39, 0
	s_add_u32 s22, s38, 0x1d6c2a00
	s_addc_u32 s23, s39, 0
	s_add_u32 s24, s38, 0x1d6c2b00
	s_addc_u32 s25, s39, 0
	s_add_u32 s28, s38, 0x1d6c2c00
	s_addc_u32 s29, s39, 0
	s_add_u32 s44, s38, 0x1d6c2d00
	s_addc_u32 s45, s39, 0
	s_add_u32 s46, s38, 0x1d6c2e00
	s_addc_u32 s47, s39, 0
	s_add_u32 s48, s38, 0x1d6c2f00
	s_addc_u32 s49, s39, 0
	s_add_u32 s50, s38, 0x1d6c3000
	s_addc_u32 s51, s39, 0
	s_add_u32 s56, s38, 0x1d6c3100
	s_addc_u32 s57, s39, 0
	s_add_u32 s58, s38, 0x1d6c3200
	s_addc_u32 s59, s39, 0
	s_mul_i32 s68, s43, s33
	s_add_u32 s60, s38, 0x1d6c3300
	s_mul_i32 s68, s68, s42
	s_addc_u32 s61, s39, 0
	s_mov_b32 s69, 1
	v_mov_b32_e32 v18, 0
	s_branch .LBB0_566

.LBB0_699:
	s_cmp_gt_i32 s41, 7
	s_cselect_b64 s[4:5], -1, 0
	s_and_b64 s[6:7], s[56:57], s[4:5]
	s_andn2_b64 vcc, exec, s[6:7]
	s_cbranch_vccnz .LBB0_749
	s_waitcnt vmcnt(0)
	s_waitcnt vmcnt(0) lgkmcnt(0)
	s_barrier
	s_and_saveexec_b64 s[6:7], s[26:27]
	s_cbranch_execz .Lmy_aa_6
	s_lshl_b32 s8, s3, 8
	s_add_u32 s8, s34, s8
	s_addc_u32 s9, s35, 0
	v_mov_b32_e32 v237, 0x1000
	v_mov_b32_e32 v236, 1
	global_atomic_add v236, v237, v236, s[8:9] offset:1024 sc0
.Lmy_aa_6:
	s_or_b64 exec, exec, s[6:7]
.LBB0_749:
	s_cmp_lt_i32 s40, 8
	s_cselect_b64 s[6:7], -1, 0
	s_and_b64 s[8:9], s[6:7], s[4:5]
	s_andn2_b64 vcc, exec, s[8:9]
	s_cbranch_vccnz .LBB0_830
	s_and_saveexec_b64 s[4:5], s[26:27]
	s_cbranch_execz .LBB0_752
	s_add_u32 s6, s38, 0x152c2000
	s_addc_u32 s7, s39, 0
	s_waitcnt lgkmcnt(0)
	s_add_u32 s10, s38, 0x4700000
	s_addc_u32 s11, s39, 0
	s_add_i32 s12, 0, 0x20000
	v_mov_b32_e32 v2, s36
	v_mov_b32_e32 v3, s37
	v_mov_b32_e32 v4, s10
	v_mov_b32_e32 v5, s11
	v_mov_b32_e32 v6, s12
	s_mov_b32 s10, 0
	ds_write_b128 v6, v[2:5]
	s_add_i32 s12, 0, 0x20010
	v_mov_b64_e32 v[4:5], s[6:7]
	s_movk_i32 s6, 0x80
	s_movk_i32 s11, 0x400
	v_mov_b32_e32 v2, s12
	s_mov_b32 s7, 4
	s_add_i32 s12, 0, 0x20018
	ds_write_b64 v2, v[4:5]
	v_mov_b32_e32 v6, s12
	v_mov_b64_e32 v[2:3], s[6:7]
	v_mov_b64_e32 v[4:5], s[10:11]
	s_add_i32 s6, 0, 0x20028
	ds_write2_b64 v6, v[2:3], v[4:5] offset1:1
	v_mov_b32_e32 v2, 4
	v_mov_b32_e32 v3, 16
	v_mov_b32_e32 v4, s6
	ds_write_b64 v4, v[2:3]
.LBB0_752:
	s_or_b64 exec, exec, s[4:5]
	s_cmpk_lt_i32 s2, 0x200
	v_mov_b32_e32 v14, v1
	s_cselect_b64 s[4:5], -1, 0
	s_cmpk_gt_i32 s2, 0x1ff
	s_waitcnt lgkmcnt(0)
	s_barrier
	s_nop 0
	v_readfirstlane_b32 s18, v14
	s_cbranch_scc1 .LBB0_754
	s_ashr_i32 s6, s2, 31
	s_lshr_b32 s6, s6, 29
	s_add_i32 s6, s2, s6
	s_ashr_i32 s7, s6, 3
	s_and_b32 s6, s6, -8
	s_sub_i32 s6, s2, s6
	s_lshl_b32 s10, s6, 6
	s_cmp_lt_i32 s6, 0
	s_mulk_i32 s6, 0x41
	s_cselect_b32 s6, s6, s10
	s_add_i32 s10, 0, 0x20018
	v_mov_b32_e32 v2, s10
	ds_read_b64 v[2:3], v2
	s_add_i32 s10, 0, 0x20020
	v_mov_b32_e32 v4, s10
	ds_read_b32 v4, v4
	s_add_i32 s6, s6, s7
	s_waitcnt lgkmcnt(1)
	v_readfirstlane_b32 s10, v3
	s_lshl_b32 s10, s10, 3
	s_abs_i32 s11, s10
	v_cvt_f32_u32_e32 v3, s11
	v_readfirstlane_b32 s7, v2
	s_sub_i32 s14, 0, s11
	s_waitcnt lgkmcnt(0)
	v_readfirstlane_b32 s12, v4
	v_rcp_iflag_f32_e32 v2, v3
	s_sub_i32 s6, s6, s12
	s_abs_i32 s13, s6
	s_xor_b32 s12, s6, s10
	v_mul_f32_e32 v2, 0x4f7ffffe, v2
	v_cvt_u32_f32_e32 v2, v2
	s_ashr_i32 s12, s12, 31
	v_readfirstlane_b32 s15, v2
	s_mul_i32 s14, s14, s15
	s_mul_hi_u32 s14, s15, s14
	s_add_i32 s15, s15, s14
	s_mul_hi_u32 s14, s13, s15
	s_mul_i32 s15, s14, s11
	s_sub_i32 s13, s13, s15
	s_add_i32 s15, s14, 1
	s_sub_i32 s16, s13, s11
	s_cmp_ge_u32 s13, s11
	s_cselect_b32 s14, s15, s14
	s_cselect_b32 s13, s16, s13
	s_add_i32 s15, s14, 1
	s_cmp_ge_u32 s13, s11
	s_cselect_b32 s11, s15, s14
	s_xor_b32 s11, s11, s12
	s_sub_i32 s11, s11, s12
	s_lshl_b32 s12, s11, 3
	s_sub_i32 s7, s7, s12
	s_min_i32 s7, s7, 8
	s_abs_i32 s13, s7
	v_cvt_f32_u32_e32 v2, s13
	s_sub_i32 s14, 0, s13
	s_mul_i32 s11, s11, s10
	s_sub_i32 s6, s6, s11
	v_rcp_iflag_f32_e32 v2, v2
	s_abs_i32 s10, s6
	s_xor_b32 s11, s6, s7
	s_ashr_i32 s11, s11, 31
	v_mul_f32_e32 v2, 0x4f7ffffe, v2
	v_cvt_u32_f32_e32 v2, v2
	s_nop 0
	v_readfirstlane_b32 s15, v2
	s_mul_i32 s14, s14, s15
	s_mul_hi_u32 s14, s15, s14
	s_add_i32 s15, s15, s14
	s_mul_hi_u32 s14, s10, s15
	s_mul_i32 s15, s14, s13
	s_sub_i32 s10, s10, s15
	s_add_i32 s15, s14, 1
	s_sub_i32 s16, s10, s13
	s_cmp_ge_u32 s10, s13
	s_cselect_b32 s14, s15, s14
	s_cselect_b32 s10, s16, s10
	s_add_i32 s15, s14, 1
	s_cmp_ge_u32 s10, s13
	s_cselect_b32 s10, s15, s14
	s_xor_b32 s10, s10, s11
	s_sub_i32 s48, s10, s11
	s_add_i32 s10, 0, 0x2002c
	v_mov_b32_e32 v2, s10
	s_add_i32 s10, 0, 0x20000
	v_mov_b32_e32 v3, s10
	s_mul_i32 s7, s48, s7
	ds_read_b32 v138, v2
	ds_read_b128 v[2:5], v3
	s_sub_i32 s6, s6, s7
	s_add_i32 s6, s6, s12
	s_ashr_i32 s7, s6, 31
	s_lshl_b64 s[10:11], s[6:7], 19
	s_ashr_i32 s49, s48, 31
	s_waitcnt lgkmcnt(0)
	v_lshl_add_u64 v[2:3], v[2:3], 0, s[10:11]
	s_lshl_b64 s[10:11], s[48:49], 19
	v_lshl_add_u64 v[4:5], v[4:5], 0, s[10:11]
	s_andn2_b64 vcc, exec, s[4:5]
	s_cbranch_vccz .LBB0_755
	s_branch .LBB0_830

.LBB0_830:
	s_cmp_gt_i32 s41, 8
	s_cselect_b64 s[4:5], -1, 0
	s_and_b64 s[6:7], s[8:9], s[4:5]
	s_andn2_b64 vcc, exec, s[6:7]
	s_cbranch_vccnz .LBB0_880
	s_waitcnt vmcnt(0)
	s_waitcnt vmcnt(0) lgkmcnt(0)
	s_barrier
	s_and_saveexec_b64 s[6:7], s[26:27]
	s_cbranch_execz .LBB0_879
	v_add_u32_e32 v239, 1, v239
	s_add_i32 s8, 0, 0x257f0
	v_mov_b32_e32 v2, s8
	s_waitcnt vmcnt(0) expcnt(0) lgkmcnt(0)
	ds_read_b32 v4, v2
	s_add_i32 s8, 0, 0x257f4
	v_mov_b32_e32 v2, s8
	ds_read_b32 v2, v2
	s_waitcnt lgkmcnt(1)
	v_cmp_ne_u32_e32 vcc, 0, v4
	s_cbranch_vccnz .LBB0_847
	s_add_u32 s8, s38, 0x1d6c2200
	s_addc_u32 s9, s39, 0
	s_add_u32 s10, s38, 0x1d6c2400
	s_addc_u32 s11, s39, 0
	s_add_u32 s12, s38, 0x1d6c2500
	s_addc_u32 s13, s39, 0
	s_add_u32 s14, s38, 0x1d6c2600
	s_addc_u32 s15, s39, 0
	s_add_u32 s16, s38, 0x1d6c2700
	s_addc_u32 s17, s39, 0
	s_add_u32 s18, s38, 0x1d6c2800
	s_addc_u32 s19, s39, 0
	s_add_u32 s20, s38, 0x1d6c2900
	s_addc_u32 s21, s39, 0
	s_add_u32 s22, s38, 0x1d6c2a00
	s_addc_u32 s23, s39, 0
	s_add_u32 s24, s38, 0x1d6c2b00
	s_addc_u32 s25, s39, 0
	s_add_u32 s28, s38, 0x1d6c2c00
	s_addc_u32 s29, s39, 0
	s_add_u32 s44, s38, 0x1d6c2d00
	s_addc_u32 s45, s39, 0
	s_add_u32 s46, s38, 0x1d6c2e00
	s_addc_u32 s47, s39, 0
	s_add_u32 s48, s38, 0x1d6c2f00
	s_addc_u32 s49, s39, 0
	s_add_u32 s50, s38, 0x1d6c3000
	s_addc_u32 s51, s39, 0
	s_add_u32 s56, s38, 0x1d6c3100
	s_addc_u32 s57, s39, 0
	s_add_u32 s58, s38, 0x1d6c3200
	s_addc_u32 s59, s39, 0
	s_mul_i32 s68, s43, s33
	s_add_u32 s60, s38, 0x1d6c3300
	s_mul_i32 s68, s68, s42
	s_addc_u32 s61, s39, 0
	s_mov_b32 s69, 1
	v_mov_b32_e32 v18, 0
	s_branch .LBB0_835

.LBB0_884:
	s_cmp_gt_i32 s41, 9
	s_cselect_b64 s[4:5], -1, 0
	s_and_b64 s[6:7], s[8:9], s[4:5]
	s_andn2_b64 vcc, exec, s[6:7]
	s_cbranch_vccnz .LBB0_934
	s_waitcnt vmcnt(0)
	s_waitcnt vmcnt(0) lgkmcnt(0)
	s_barrier
	s_and_saveexec_b64 s[6:7], s[26:27]
	s_cbranch_execz .Lmy_aa_8
	s_lshl_b32 s8, s3, 8
	s_add_u32 s8, s34, s8
	s_addc_u32 s9, s35, 0
	v_mov_b32_e32 v237, 0x1000
	v_mov_b32_e32 v236, 1
	global_atomic_add v236, v237, v236, s[8:9] offset:1024 sc0
.Lmy_aa_8:
	s_or_b64 exec, exec, s[6:7]
.LBB0_934:
	s_cmp_lt_i32 s40, 10
	s_cselect_b64 s[6:7], -1, 0
	s_and_b64 s[8:9], s[6:7], s[4:5]
	s_andn2_b64 vcc, exec, s[8:9]
	s_cbranch_vccnz .LBB0_1011
	s_and_saveexec_b64 s[4:5], s[26:27]
	s_cbranch_execz .LBB0_937
	s_waitcnt lgkmcnt(0)
	s_add_u32 s10, s38, 0x53c2000
	s_addc_u32 s11, s39, 0
	s_add_u32 s12, s38, 0xb00000
	s_addc_u32 s13, s39, 0
	s_add_u32 s6, s38, 0x97c2000
	s_addc_u32 s7, s39, 0
	v_mov_b32_e32 v4, s12
	s_add_i32 s12, 0, 0x20000
	v_mov_b32_e32 v2, s10
	v_mov_b32_e32 v3, s11
	v_mov_b32_e32 v5, s13
	v_mov_b32_e32 v6, s12
	s_mov_b32 s10, 0
	ds_write_b128 v6, v[2:5]
	s_add_i32 s12, 0, 0x20010
	v_mov_b64_e32 v[4:5], s[6:7]
	s_movk_i32 s6, 0x80
	s_movk_i32 s11, 0xb00
	v_mov_b32_e32 v2, s12
	s_mov_b32 s7, 22
	s_add_i32 s12, 0, 0x20018
	ds_write_b64 v2, v[4:5]
	v_mov_b32_e32 v6, s12
	v_mov_b64_e32 v[2:3], s[6:7]
	v_mov_b64_e32 v[4:5], s[10:11]
	s_add_i32 s6, 0, 0x20028
	ds_write2_b64 v6, v[2:3], v[4:5] offset1:1
	v_mov_b32_e32 v2, 1
	v_mov_b32_e32 v3, 16
	v_mov_b32_e32 v4, s6
	ds_write_b64 v4, v[2:3]
.LBB0_937:
	s_or_b64 exec, exec, s[4:5]
	s_cmpk_lt_i32 s2, 0xb00
	v_mov_b32_e32 v14, v1
	s_cselect_b64 s[4:5], -1, 0
	s_cmpk_gt_i32 s2, 0xaff
	s_waitcnt lgkmcnt(0)
	s_barrier
	s_nop 0
	v_readfirstlane_b32 s12, v14
	s_cbranch_scc1 .LBB0_939
	s_ashr_i32 s6, s2, 31
	s_lshr_b32 s6, s6, 29
	s_add_i32 s6, s2, s6
	s_ashr_i32 s7, s6, 3
	s_and_b32 s6, s6, -8
	s_sub_i32 s6, s2, s6
	s_cmp_lt_i32 s6, 0
	s_movk_i32 s10, 0x161
	s_cselect_b32 s10, s10, 0x160
	s_add_i32 s11, 0, 0x20018
	v_mov_b32_e32 v2, s11
	ds_read_b64 v[2:3], v2
	s_add_i32 s11, 0, 0x20020
	v_mov_b32_e32 v4, s11
	ds_read_b32 v4, v4
	s_mul_i32 s6, s6, s10
	s_waitcnt lgkmcnt(1)
	v_readfirstlane_b32 s11, v3
	s_lshl_b32 s11, s11, 3
	s_abs_i32 s13, s11
	v_cvt_f32_u32_e32 v3, s13
	s_add_i32 s6, s6, s7
	v_readfirstlane_b32 s7, v2
	s_sub_i32 s15, 0, s13
	v_rcp_iflag_f32_e32 v2, v3
	s_waitcnt lgkmcnt(0)
	v_readfirstlane_b32 s10, v4
	s_sub_i32 s6, s6, s10
	s_abs_i32 s14, s6
	v_mul_f32_e32 v2, 0x4f7ffffe, v2
	v_cvt_u32_f32_e32 v2, v2
	s_xor_b32 s10, s6, s11
	s_ashr_i32 s10, s10, 31
	v_readfirstlane_b32 s16, v2
	s_mul_i32 s15, s15, s16
	s_mul_hi_u32 s15, s16, s15
	s_add_i32 s16, s16, s15
	s_mul_hi_u32 s15, s14, s16
	s_mul_i32 s16, s15, s13
	s_sub_i32 s14, s14, s16
	s_add_i32 s16, s15, 1
	s_sub_i32 s17, s14, s13
	s_cmp_ge_u32 s14, s13
	s_cselect_b32 s15, s16, s15
	s_cselect_b32 s14, s17, s14
	s_add_i32 s16, s15, 1
	s_cmp_ge_u32 s14, s13
	s_cselect_b32 s13, s16, s15
	s_xor_b32 s13, s13, s10
	s_sub_i32 s10, s13, s10
	s_lshl_b32 s13, s10, 3
	s_sub_i32 s7, s7, s13
	s_min_i32 s7, s7, 8
	s_abs_i32 s14, s7
	v_cvt_f32_u32_e32 v2, s14
	s_sub_i32 s15, 0, s14
	s_mul_i32 s10, s10, s11
	s_sub_i32 s6, s6, s10
	v_rcp_iflag_f32_e32 v2, v2
	s_abs_i32 s11, s6
	s_xor_b32 s10, s6, s7
	s_ashr_i32 s10, s10, 31
	v_mul_f32_e32 v2, 0x4f7ffffe, v2
	v_cvt_u32_f32_e32 v2, v2
	s_nop 0
	v_readfirstlane_b32 s16, v2
	s_mul_i32 s15, s15, s16
	s_mul_hi_u32 s15, s16, s15
	s_add_i32 s16, s16, s15
	s_mul_hi_u32 s15, s11, s16
	s_mul_i32 s16, s15, s14
	s_sub_i32 s11, s11, s16
	s_add_i32 s16, s15, 1
	s_sub_i32 s17, s11, s14
	s_cmp_ge_u32 s11, s14
	s_cselect_b32 s15, s16, s15
	s_cselect_b32 s11, s17, s11
	s_add_i32 s16, s15, 1
	s_cmp_ge_u32 s11, s14
	s_cselect_b32 s11, s16, s15
	s_xor_b32 s11, s11, s10
	s_sub_i32 s50, s11, s10
	s_add_i32 s10, 0, 0x2002c
	v_mov_b32_e32 v2, s10
	s_add_i32 s10, 0, 0x20000
	v_mov_b32_e32 v3, s10
	s_mul_i32 s7, s50, s7
	ds_read_b32 v138, v2
	ds_read_b128 v[2:5], v3
	s_sub_i32 s6, s6, s7
	s_add_i32 s6, s6, s13
	s_ashr_i32 s7, s6, 31
	s_lshl_b64 s[10:11], s[6:7], 19
	s_ashr_i32 s51, s50, 31
	s_waitcnt lgkmcnt(0)
	v_lshl_add_u64 v[2:3], v[2:3], 0, s[10:11]
	s_lshl_b64 s[10:11], s[50:51], 19
	v_lshl_add_u64 v[4:5], v[4:5], 0, s[10:11]
	s_andn2_b64 vcc, exec, s[4:5]
	s_cbranch_vccz .LBB0_940
	s_branch .LBB0_1011

.LBB0_940:
	v_ashrrev_i32_e32 v7, 31, v14
	v_lshrrev_b32_e32 v7, 26, v7
	v_add_u32_e32 v7, v14, v7
	v_ashrrev_i32_e32 v15, 6, v7
	v_bfe_i32 v7, v14, 27, 1
	v_lshlrev_b32_e32 v6, 4, v14
	v_lshrrev_b32_e32 v7, 22, v7
	v_add_u32_e32 v7, v6, v7
	v_and_b32_e32 v7, 0xfffffc00, v7
	v_sub_u32_e32 v7, v6, v7
	v_lshrrev_b32_e32 v8, 4, v7
	v_bitop3_b32 v8, v8, v7, 32 bitop3:0x6c
	v_ashrrev_i32_e32 v7, 31, v7
	v_lshrrev_b32_e32 v7, 26, v7
	v_add_u32_e32 v7, v8, v7
	v_ashrrev_i32_e32 v16, 6, v7
	v_lshlrev_b32_e32 v9, 3, v15
	v_mul_i32_i24_e32 v10, 64, v16
	v_and_b32_e32 v9, -16, v9
	v_sub_u32_e32 v8, v8, v10
	v_mov_b32_e32 v10, 1
	v_add_u32_e32 v7, v16, v9
	v_lshlrev_b32_e32 v9, 5, v15
	v_ashrrev_i16_sdwa v8, v10, sext(v8) dst_sel:DWORD dst_unused:UNUSED_PAD src0_sel:DWORD src1_sel:BYTE_0
	v_and_b32_e32 v9, 32, v9
	v_bfe_i32 v17, v8, 0, 16
	v_and_b32_e32 v12, 3, v16
	s_mov_b32 s5, 0x1fffe0
	v_add_lshl_u32 v9, v9, v17, 1
	v_add_u32_e32 v6, 0x2000, v6
	v_lshlrev_b32_e32 v8, 1, v7
	v_lshrrev_b32_e32 v11, 2, v7
	v_and_or_b32 v12, v7, s5, v12
	v_lshl_add_u32 v130, v7, 11, v9
	v_ashrrev_i32_e32 v7, 31, v6
	v_lshrrev_b32_e32 v7, 22, v7
	v_add_u32_e32 v7, v6, v7
	v_ashrrev_i32_e32 v18, 10, v7
	v_mul_i32_i24_e32 v7, 0x400, v18
	v_sub_u32_e32 v6, v6, v7
	v_and_b32_e32 v8, 24, v8
	v_and_b32_e32 v11, 4, v11
	v_lshrrev_b32_e32 v7, 4, v6
	v_or3_b32 v8, v12, v11, v8
	v_bitop3_b32 v6, v7, v6, 32 bitop3:0x6c
	v_lshl_add_u32 v132, v8, 11, v9
	v_ashrrev_i32_e32 v8, 31, v6
	v_lshrrev_b32_e32 v8, 26, v8
	v_add_u32_e32 v8, v6, v8
	v_lshlrev_b32_e32 v7, 3, v18
	v_ashrrev_i32_e32 v19, 6, v8
	v_and_b32_e32 v8, 0xc0, v8
	v_and_b32_e32 v7, -16, v7
	v_sub_u32_e32 v6, v6, v8
	s_ashr_i32 s4, s12, 6
	v_add_u32_e32 v7, v19, v7
	v_ashrrev_i16_sdwa v6, v10, sext(v6) dst_sel:DWORD dst_unused:UNUSED_PAD src0_sel:DWORD src1_sel:BYTE_0
	v_lshlrev_b32_e32 v9, 5, v18
	v_bfe_i32 v20, v6, 0, 16
	v_lshlrev_b32_e32 v6, 1, v7
	v_lshrrev_b32_e32 v8, 2, v7
	v_and_b32_e32 v10, 3, v19
	s_lshl_b32 s29, s4, 10
	v_and_b32_e32 v9, 32, v9
	v_and_b32_e32 v6, 24, v6
	v_and_b32_e32 v8, 4, v8
	v_and_or_b32 v10, v7, s5, v10
	s_add_i32 s51, s29, 0
	v_or3_b32 v6, v10, v8, v6
	v_add_lshl_u32 v8, v9, v20, 1
	s_add_i32 m0, s51, 0x10000
	v_readfirstlane_b32 s10, v4
	v_readfirstlane_b32 s11, v5
	v_lshl_add_u32 v136, v6, 11, v8
	v_lshl_add_u32 v134, v7, 11, v8
	s_add_i32 s60, s51, 0x2000
	s_add_i32 s61, s51, 0x4000
	s_add_i32 s62, s51, 0x6000
	s_and_saveexec_b64 s[96:97], s[26:27]
	s_cbranch_execz .Lmy_w_8
	v_mov_b32_e32 v238, 0x257f0
	ds_read2_b32 v[234:235], v238 offset1:1
	v_add_u32_e32 v239, 1, v239
	s_add_u32 s98, s38, 0x1d6c5400
	s_addc_u32 s99, s39, 0
	s_mov_b32 s94, 0
	s_waitcnt vmcnt(0) lgkmcnt(0)
	v_mul_u32_u24_e32 v238, v239, v234
	v_add_u32_e32 v236, 1, v236
	v_mul_u32_u24_e32 v237, v239, v235
	v_cmp_eq_u32_e32 vcc, v236, v238
	v_mov_b32_e32 v238, 0
	s_cbranch_vccz .Lmy_ws_8
	buffer_wbl2 sc1
	s_waitcnt vmcnt(0)
	v_mov_b32_e32 v234, 0x1d6c5000
	v_mov_b32_e32 v235, 1
	global_atomic_add v234, v235, s[38:39] offset:1024

.LBB0_1011:
	s_cmp_gt_i32 s41, 10
	s_cselect_b64 s[4:5], -1, 0
	s_and_b64 s[6:7], s[8:9], s[4:5]
	s_andn2_b64 vcc, exec, s[6:7]
	s_cbranch_vccnz .LBB0_1061
	s_waitcnt vmcnt(0)
	s_waitcnt vmcnt(0) lgkmcnt(0)
	s_barrier
	s_and_saveexec_b64 s[6:7], s[26:27]
	s_cbranch_execz .Lmy_aa_9
	s_lshl_b32 s8, s3, 8
	s_add_u32 s8, s34, s8
	s_addc_u32 s9, s35, 0
	v_mov_b32_e32 v237, 0x1000
	v_mov_b32_e32 v236, 1
	global_atomic_add v236, v237, v236, s[8:9] offset:1024 sc0
.Lmy_aa_9:
	s_or_b64 exec, exec, s[6:7]
.LBB0_1061:
	s_cmp_lt_i32 s40, 11
	s_cselect_b64 s[6:7], -1, 0
	s_and_b64 s[8:9], s[6:7], s[4:5]
	s_andn2_b64 vcc, exec, s[8:9]
	s_cbranch_vccnz .LBB0_1142
	s_and_saveexec_b64 s[4:5], s[26:27]
	s_cbranch_execz .LBB0_1064
	s_add_u32 s6, s38, 0x152c2000
	s_addc_u32 s7, s39, 0
	s_waitcnt lgkmcnt(0)
	s_add_u32 s10, s38, 0x97c2000
	s_addc_u32 s11, s39, 0
	s_add_u32 s12, s38, 0x3180000
	s_addc_u32 s13, s39, 0
	v_mov_b32_e32 v4, s12
	s_add_i32 s12, 0, 0x20000
	v_mov_b32_e32 v2, s10
	v_mov_b32_e32 v3, s11
	v_mov_b32_e32 v5, s13
	v_mov_b32_e32 v6, s12
	s_mov_b32 s10, 0
	ds_write_b128 v6, v[2:5]
	s_add_i32 s12, 0, 0x20010
	v_mov_b64_e32 v[4:5], s[6:7]
	s_movk_i32 s6, 0x80
	s_movk_i32 s11, 0x400
	v_mov_b32_e32 v2, s12
	s_mov_b32 s7, 4
	s_add_i32 s12, 0, 0x20018
	ds_write_b64 v2, v[4:5]
	v_mov_b32_e32 v6, s12
	v_mov_b64_e32 v[2:3], s[6:7]
	v_mov_b64_e32 v[4:5], s[10:11]
	s_add_i32 s6, 0, 0x20028
	ds_write2_b64 v6, v[2:3], v[4:5] offset1:1
	v_mov_b32_e32 v2, 4
	v_mov_b32_e32 v3, 44
	v_mov_b32_e32 v4, s6
	ds_write_b64 v4, v[2:3]
.LBB0_1064:
	s_or_b64 exec, exec, s[4:5]
	s_cmpk_lt_i32 s2, 0x200
	v_mov_b32_e32 v12, v1
	s_cselect_b64 s[4:5], -1, 0
	s_cmpk_gt_i32 s2, 0x1ff
	s_waitcnt lgkmcnt(0)
	s_barrier
	s_nop 0
	v_readfirstlane_b32 s6, v12
	s_cbranch_scc1 .LBB0_1066
	s_ashr_i32 s7, s2, 31
	s_lshr_b32 s7, s7, 29
	s_add_i32 s7, s2, s7
	s_ashr_i32 s10, s7, 3
	s_and_b32 s7, s7, -8
	s_sub_i32 s7, s2, s7
	s_lshl_b32 s11, s7, 6
	s_cmp_lt_i32 s7, 0
	s_mulk_i32 s7, 0x41
	s_cselect_b32 s7, s7, s11
	s_add_i32 s11, 0, 0x20018
	v_mov_b32_e32 v2, s11
	ds_read_b64 v[2:3], v2
	s_add_i32 s11, 0, 0x20020
	v_mov_b32_e32 v4, s11
	ds_read_b32 v4, v4
	s_add_i32 s7, s7, s10
	s_waitcnt lgkmcnt(1)
	v_readfirstlane_b32 s11, v3
	s_lshl_b32 s11, s11, 3
	s_abs_i32 s12, s11
	v_cvt_f32_u32_e32 v3, s12
	v_readfirstlane_b32 s10, v2
	s_sub_i32 s15, 0, s12
	s_waitcnt lgkmcnt(0)
	v_readfirstlane_b32 s13, v4
	v_rcp_iflag_f32_e32 v2, v3
	s_sub_i32 s7, s7, s13
	s_abs_i32 s14, s7
	s_xor_b32 s13, s7, s11
	v_mul_f32_e32 v2, 0x4f7ffffe, v2
	v_cvt_u32_f32_e32 v2, v2
	s_ashr_i32 s13, s13, 31
	v_readfirstlane_b32 s16, v2
	s_mul_i32 s15, s15, s16
	s_mul_hi_u32 s15, s16, s15
	s_add_i32 s16, s16, s15
	s_mul_hi_u32 s15, s14, s16
	s_mul_i32 s16, s15, s12
	s_sub_i32 s14, s14, s16
	s_add_i32 s16, s15, 1
	s_sub_i32 s17, s14, s12
	s_cmp_ge_u32 s14, s12
	s_cselect_b32 s15, s16, s15
	s_cselect_b32 s14, s17, s14
	s_add_i32 s16, s15, 1
	s_cmp_ge_u32 s14, s12
	s_cselect_b32 s12, s16, s15
	s_xor_b32 s12, s12, s13
	s_sub_i32 s12, s12, s13
	s_lshl_b32 s13, s12, 3
	s_sub_i32 s10, s10, s13
	s_min_i32 s10, s10, 8
	s_abs_i32 s14, s10
	v_cvt_f32_u32_e32 v2, s14
	s_sub_i32 s15, 0, s14
	s_mul_i32 s12, s12, s11
	s_sub_i32 s7, s7, s12
	v_rcp_iflag_f32_e32 v2, v2
	s_abs_i32 s11, s7
	s_xor_b32 s12, s7, s10
	s_ashr_i32 s12, s12, 31
	v_mul_f32_e32 v2, 0x4f7ffffe, v2
	v_cvt_u32_f32_e32 v2, v2
	s_nop 0
	v_readfirstlane_b32 s16, v2
	s_mul_i32 s15, s15, s16
	s_mul_hi_u32 s15, s16, s15
	s_add_i32 s16, s16, s15
	s_mul_hi_u32 s15, s11, s16
	s_mul_i32 s16, s15, s14
	s_sub_i32 s11, s11, s16
	s_add_i32 s16, s15, 1
	s_sub_i32 s17, s11, s14
	s_cmp_ge_u32 s11, s14
	s_cselect_b32 s15, s16, s15
	s_cselect_b32 s11, s17, s11
	s_add_i32 s16, s15, 1
	s_cmp_ge_u32 s11, s14
	s_cselect_b32 s11, s16, s15
	s_xor_b32 s11, s11, s12
	s_sub_i32 s76, s11, s12
	s_add_i32 s11, 0, 0x2002c
	v_mov_b32_e32 v2, s11
	s_add_i32 s11, 0, 0x20000
	v_mov_b32_e32 v3, s11
	ds_read_b32 v156, v2
	ds_read_b128 v[2:5], v3
	s_mul_i32 s10, s76, s10
	s_sub_i32 s7, s7, s10
	s_add_i32 s28, s7, s13
	s_mul_hi_i32 s11, s28, 0x160000
	s_mul_i32 s10, s28, 0x160000
	s_waitcnt lgkmcnt(0)
	v_lshl_add_u64 v[150:151], v[2:3], 0, s[10:11]
	s_mul_hi_i32 s11, s76, 0x160000
	s_mul_i32 s10, s76, 0x160000
	v_lshl_add_u64 v[2:3], v[4:5], 0, s[10:11]
	s_andn2_b64 vcc, exec, s[4:5]
	s_cbranch_vccz .LBB0_1067
	s_branch .LBB0_1142

.LBB0_1067:
	v_ashrrev_i32_e32 v5, 31, v12
	v_lshrrev_b32_e32 v5, 26, v5
	v_add_u32_e32 v5, v12, v5
	v_ashrrev_i32_e32 v13, 6, v5
	v_bfe_i32 v5, v12, 27, 1
	v_lshlrev_b32_e32 v4, 4, v12
	v_lshrrev_b32_e32 v5, 22, v5
	v_add_u32_e32 v5, v4, v5
	v_and_b32_e32 v5, 0xfffffc00, v5
	v_sub_u32_e32 v5, v4, v5
	v_lshrrev_b32_e32 v6, 4, v5
	v_bitop3_b32 v6, v6, v5, 32 bitop3:0x6c
	v_ashrrev_i32_e32 v5, 31, v5
	v_lshrrev_b32_e32 v5, 26, v5
	v_lshlrev_b32_e32 v7, 3, v13
	v_add_u32_e32 v5, v6, v5
	v_and_b32_e32 v7, -16, v7
	v_ashrrev_i32_e32 v14, 6, v5
	v_add_u32_e32 v5, v14, v7
	v_lshlrev_b32_e32 v7, 5, v13
	v_and_b32_e32 v15, 32, v7
	v_mul_i32_i24_e32 v7, 64, v14
	v_sub_u32_e32 v6, v6, v7
	v_mov_b32_e32 v7, 1
	v_ashrrev_i16_sdwa v6, v7, sext(v6) dst_sel:DWORD dst_unused:UNUSED_PAD src0_sel:DWORD src1_sel:BYTE_0
	v_lshlrev_b32_e32 v8, 1, v5
	v_lshrrev_b32_e32 v9, 2, v5
	v_and_b32_e32 v10, 3, v14
	s_mov_b32 s5, 0xffffe0
	v_bfe_i32 v16, v6, 0, 16
	v_and_b32_e32 v8, 24, v8
	v_and_b32_e32 v9, 4, v9
	v_and_or_b32 v10, v5, s5, v10
	s_movk_i32 s7, 0xb00
	v_add_u32_e32 v6, v15, v16
	v_or3_b32 v8, v10, v9, v8
	v_mul_lo_u32 v5, v5, s7
	v_add_lshl_u32 v130, v6, v5, 1
	v_mul_u32_u24_e32 v5, 0xb00, v8
	v_add_u32_e32 v4, 0x2000, v4
	v_add_lshl_u32 v132, v5, v6, 1
	v_ashrrev_i32_e32 v5, 31, v4
	v_lshrrev_b32_e32 v5, 22, v5
	v_add_u32_e32 v5, v4, v5
	v_ashrrev_i32_e32 v17, 10, v5
	v_mul_i32_i24_e32 v5, 0x400, v17
	v_sub_u32_e32 v4, v4, v5
	v_lshrrev_b32_e32 v5, 4, v4
	v_bitop3_b32 v4, v5, v4, 32 bitop3:0x6c
	v_ashrrev_i32_e32 v6, 31, v4
	v_lshrrev_b32_e32 v6, 26, v6
	v_lshlrev_b32_e32 v5, 3, v17
	v_add_u32_e32 v6, v4, v6
	v_and_b32_e32 v5, -16, v5
	v_ashrrev_i32_e32 v19, 6, v6
	v_and_b32_e32 v6, 0xc0, v6
	v_add_u32_e32 v5, v19, v5
	v_lshlrev_b32_e32 v8, 5, v17
	v_sub_u32_e32 v4, v4, v6
	s_ashr_i32 s4, s6, 6
	v_and_b32_e32 v18, 32, v8
	v_ashrrev_i16_sdwa v4, v7, sext(v4) dst_sel:DWORD dst_unused:UNUSED_PAD src0_sel:DWORD src1_sel:BYTE_0
	v_lshlrev_b32_e32 v6, 1, v5
	v_lshrrev_b32_e32 v7, 2, v5
	v_and_b32_e32 v8, 3, v19
	v_bfe_i32 v20, v4, 0, 16
	v_and_b32_e32 v6, 24, v6
	v_and_b32_e32 v7, 4, v7
	v_and_or_b32 v8, v5, s5, v8
	s_lshl_b32 s23, s4, 10
	v_add_u32_e32 v4, v18, v20
	v_or3_b32 v6, v8, v7, v6
	v_mul_lo_u32 v5, v5, s7
	s_add_i32 s46, s23, 0
	v_add_lshl_u32 v134, v4, v5, 1
	v_mul_u32_u24_e32 v5, 0xb00, v6
	s_add_i32 m0, s46, 0x10000
	v_readfirstlane_b32 s10, v2
	v_readfirstlane_b32 s11, v3
	v_add_lshl_u32 v136, v5, v4, 1
	s_add_i32 s47, s46, 0x2000
	s_add_i32 s48, s46, 0x4000
	s_add_i32 s49, s46, 0x6000
	s_ashr_i32 s5, s6, 8
	s_and_saveexec_b64 s[96:97], s[26:27]
	s_cbranch_execz .Lmy_w_9
	v_mov_b32_e32 v238, 0x257f0
	ds_read2_b32 v[234:235], v238 offset1:1
	v_add_u32_e32 v239, 1, v239
	s_add_u32 s98, s38, 0x1d6c5400
	s_addc_u32 s99, s39, 0
	s_mov_b32 s94, 0
	s_waitcnt vmcnt(0) lgkmcnt(0)
	v_mul_u32_u24_e32 v238, v239, v234
	v_add_u32_e32 v236, 1, v236
	v_mul_u32_u24_e32 v237, v239, v235
	v_cmp_eq_u32_e32 vcc, v236, v238
	v_mov_b32_e32 v238, 0
	s_cbranch_vccz .Lmy_ws_9
	buffer_wbl2 sc1
	s_waitcnt vmcnt(0)
	v_mov_b32_e32 v234, 0x1d6c5000
	v_mov_b32_e32 v235, 1
	global_atomic_add v234, v235, s[38:39] offset:1024

.LBB0_1142:
	s_cmp_gt_i32 s41, 11
	s_cselect_b64 s[4:5], -1, 0
	s_and_b64 s[6:7], s[8:9], s[4:5]
	s_andn2_b64 vcc, exec, s[6:7]
	s_cbranch_vccnz .LBB0_1192
	s_waitcnt vmcnt(0)
	s_waitcnt vmcnt(0) lgkmcnt(0)
	s_barrier
	s_and_saveexec_b64 s[6:7], s[26:27]
	s_cbranch_execz .LBB0_1191
	v_add_u32_e32 v239, 1, v239
	s_add_i32 s8, 0, 0x257f0
	v_mov_b32_e32 v2, s8
	s_waitcnt vmcnt(0) expcnt(0) lgkmcnt(0)
	ds_read_b32 v4, v2
	s_add_i32 s8, 0, 0x257f4
	v_mov_b32_e32 v2, s8
	ds_read_b32 v2, v2
	s_waitcnt lgkmcnt(1)
	v_cmp_ne_u32_e32 vcc, 0, v4
	s_cbranch_vccnz .LBB0_1159
	s_add_u32 s8, s38, 0x1d6c2200
	s_addc_u32 s9, s39, 0
	s_add_u32 s10, s38, 0x1d6c2400
	s_addc_u32 s11, s39, 0
	s_add_u32 s12, s38, 0x1d6c2500
	s_addc_u32 s13, s39, 0
	s_add_u32 s14, s38, 0x1d6c2600
	s_addc_u32 s15, s39, 0
	s_add_u32 s16, s38, 0x1d6c2700
	s_addc_u32 s17, s39, 0
	s_add_u32 s18, s38, 0x1d6c2800
	s_addc_u32 s19, s39, 0
	s_add_u32 s20, s38, 0x1d6c2900
	s_addc_u32 s21, s39, 0
	s_add_u32 s22, s38, 0x1d6c2a00
	s_addc_u32 s23, s39, 0
	s_add_u32 s24, s38, 0x1d6c2b00
	s_addc_u32 s25, s39, 0
	s_add_u32 s28, s38, 0x1d6c2c00
	s_addc_u32 s29, s39, 0
	s_add_u32 s44, s38, 0x1d6c2d00
	s_addc_u32 s45, s39, 0
	s_add_u32 s46, s38, 0x1d6c2e00
	s_addc_u32 s47, s39, 0
	s_add_u32 s48, s38, 0x1d6c2f00
	s_addc_u32 s49, s39, 0
	s_add_u32 s50, s38, 0x1d6c3000
	s_addc_u32 s51, s39, 0
	s_add_u32 s56, s38, 0x1d6c3100
	s_addc_u32 s57, s39, 0
	s_add_u32 s58, s38, 0x1d6c3200
	s_addc_u32 s59, s39, 0
	s_mul_i32 s68, s43, s33
	s_add_u32 s60, s38, 0x1d6c3300
	s_mul_i32 s68, s68, s42
	s_addc_u32 s61, s39, 0
	s_mov_b32 s69, 1
	v_mov_b32_e32 v18, 0
	s_branch .LBB0_1147

.LBB0_1196:
	s_cmp_gt_i32 s41, 12
	s_cselect_b64 s[4:5], -1, 0
	s_and_b64 s[6:7], s[8:9], s[4:5]
	s_andn2_b64 vcc, exec, s[6:7]
	s_cbranch_vccnz .LBB0_1246
	s_waitcnt vmcnt(0)
	s_waitcnt vmcnt(0) lgkmcnt(0)
	s_barrier
	s_and_saveexec_b64 s[6:7], s[26:27]
	s_cbranch_execz .Lmy_aa_11
	s_lshl_b32 s8, s3, 8
	s_add_u32 s8, s34, s8
	s_addc_u32 s9, s35, 0
	v_mov_b32_e32 v237, 0x1000
	v_mov_b32_e32 v236, 1
	global_atomic_add v236, v237, v236, s[8:9] offset:1024 sc0
.Lmy_aa_11:
	s_or_b64 exec, exec, s[6:7]
.LBB0_1246:
	s_cmp_lt_i32 s40, 13
	s_cselect_b64 s[6:7], -1, 0
	s_and_b64 s[8:9], s[6:7], s[4:5]
	s_andn2_b64 vcc, exec, s[8:9]
	s_cbranch_vccnz .LBB0_1323
	s_and_saveexec_b64 s[4:5], s[26:27]
	s_cbranch_execz .LBB0_1249
	s_waitcnt lgkmcnt(0)
	s_add_u32 s10, s38, 0x53c2000
	s_addc_u32 s11, s39, 0
	s_add_u32 s12, s38, 0x1600000
	s_addc_u32 s13, s39, 0
	s_add_u32 s6, s38, 0x97c2000
	s_addc_u32 s7, s39, 0
	v_mov_b32_e32 v4, s12
	s_add_i32 s12, 0, 0x20000
	v_mov_b32_e32 v2, s10
	v_mov_b32_e32 v3, s11
	v_mov_b32_e32 v5, s13
	v_mov_b32_e32 v6, s12
	s_mov_b32 s10, 0
	ds_write_b128 v6, v[2:5]
	s_add_i32 s12, 0, 0x20010
	v_mov_b64_e32 v[4:5], s[6:7]
	s_movk_i32 s6, 0x80
	s_movk_i32 s11, 0xb00
	v_mov_b32_e32 v2, s12
	s_mov_b32 s7, 22
	s_add_i32 s12, 0, 0x20018
	ds_write_b64 v2, v[4:5]
	v_mov_b32_e32 v6, s12
	v_mov_b64_e32 v[2:3], s[6:7]
	v_mov_b64_e32 v[4:5], s[10:11]
	s_add_i32 s6, 0, 0x20028
	ds_write2_b64 v6, v[2:3], v[4:5] offset1:1
	v_mov_b32_e32 v2, 1
	v_mov_b32_e32 v3, 16
	v_mov_b32_e32 v4, s6
	ds_write_b64 v4, v[2:3]

.LBB0_1323:
	s_cmp_gt_i32 s41, 13
	s_cselect_b64 s[4:5], -1, 0
	s_and_b64 s[6:7], s[8:9], s[4:5]
	s_andn2_b64 vcc, exec, s[6:7]
	s_cbranch_vccnz .LBB0_1373
	s_waitcnt vmcnt(0)
	s_waitcnt vmcnt(0) lgkmcnt(0)
	s_barrier
	s_and_saveexec_b64 s[6:7], s[26:27]
	s_cbranch_execz .Lmy_aa_12
	s_lshl_b32 s8, s3, 8
	s_add_u32 s8, s34, s8
	s_addc_u32 s9, s35, 0
	v_mov_b32_e32 v237, 0x1000
	v_mov_b32_e32 v236, 1
	global_atomic_add v236, v237, v236, s[8:9] offset:1024 sc0
.Lmy_aa_12:
	s_or_b64 exec, exec, s[6:7]
.LBB0_1373:
	s_cmp_lt_i32 s40, 14
	s_cselect_b64 s[6:7], -1, 0
	s_and_b64 s[8:9], s[6:7], s[4:5]
	s_andn2_b64 vcc, exec, s[8:9]
	s_cbranch_vccnz .LBB0_1454
	s_and_saveexec_b64 s[4:5], s[26:27]
	s_cbranch_execz .LBB0_1376
	s_add_u32 s6, s38, 0x152c2000
	s_addc_u32 s7, s39, 0
	s_waitcnt lgkmcnt(0)
	s_add_u32 s10, s38, 0x97c2000
	s_addc_u32 s11, s39, 0
	s_add_u32 s12, s38, 0x3700000
	s_addc_u32 s13, s39, 0
	v_mov_b32_e32 v4, s12
	s_add_i32 s12, 0, 0x20000
	v_mov_b32_e32 v2, s10
	v_mov_b32_e32 v3, s11
	v_mov_b32_e32 v5, s13
	v_mov_b32_e32 v6, s12
	s_mov_b32 s10, 0
	ds_write_b128 v6, v[2:5]
	s_add_i32 s12, 0, 0x20010
	v_mov_b64_e32 v[4:5], s[6:7]
	s_movk_i32 s6, 0x80
	s_movk_i32 s11, 0x400
	v_mov_b32_e32 v2, s12
	s_mov_b32 s7, 4
	s_add_i32 s12, 0, 0x20018
	ds_write_b64 v2, v[4:5]
	v_mov_b32_e32 v6, s12
	v_mov_b64_e32 v[2:3], s[6:7]
	v_mov_b64_e32 v[4:5], s[10:11]
	s_add_i32 s6, 0, 0x20028
	ds_write2_b64 v6, v[2:3], v[4:5] offset1:1
	v_mov_b32_e32 v2, 4
	v_mov_b32_e32 v3, 44
	v_mov_b32_e32 v4, s6
	ds_write_b64 v4, v[2:3]

.LBB0_1454:
	s_cmp_gt_i32 s41, 14
	s_cselect_b64 s[4:5], -1, 0
	s_and_b64 s[6:7], s[8:9], s[4:5]
	s_andn2_b64 vcc, exec, s[6:7]
	s_cbranch_vccnz .LBB0_1504
	s_waitcnt vmcnt(0)
	s_waitcnt vmcnt(0) lgkmcnt(0)
	s_barrier
	s_and_saveexec_b64 s[6:7], s[26:27]
	s_cbranch_execz .LBB0_1503
	v_add_u32_e32 v239, 1, v239
	s_add_i32 s8, 0, 0x257f0
	v_mov_b32_e32 v2, s8
	s_waitcnt vmcnt(0) expcnt(0) lgkmcnt(0)
	ds_read_b32 v4, v2
	s_add_i32 s8, 0, 0x257f4
	v_mov_b32_e32 v2, s8
	ds_read_b32 v2, v2
	s_waitcnt lgkmcnt(1)
	v_cmp_ne_u32_e32 vcc, 0, v4
	s_cbranch_vccnz .LBB0_1471
	s_add_u32 s8, s38, 0x1d6c2200
	s_addc_u32 s9, s39, 0
	s_add_u32 s10, s38, 0x1d6c2400
	s_addc_u32 s11, s39, 0
	s_add_u32 s12, s38, 0x1d6c2500
	s_addc_u32 s13, s39, 0
	s_add_u32 s14, s38, 0x1d6c2600
	s_addc_u32 s15, s39, 0
	s_add_u32 s16, s38, 0x1d6c2700
	s_addc_u32 s17, s39, 0
	s_add_u32 s18, s38, 0x1d6c2800
	s_addc_u32 s19, s39, 0
	s_add_u32 s20, s38, 0x1d6c2900
	s_addc_u32 s21, s39, 0
	s_add_u32 s22, s38, 0x1d6c2a00
	s_addc_u32 s23, s39, 0
	s_add_u32 s24, s38, 0x1d6c2b00
	s_addc_u32 s25, s39, 0
	s_add_u32 s28, s38, 0x1d6c2c00
	s_addc_u32 s29, s39, 0
	s_add_u32 s44, s38, 0x1d6c2d00
	s_addc_u32 s45, s39, 0
	s_add_u32 s46, s38, 0x1d6c2e00
	s_addc_u32 s47, s39, 0
	s_add_u32 s48, s38, 0x1d6c2f00
	s_addc_u32 s49, s39, 0
	s_add_u32 s50, s38, 0x1d6c3000
	s_addc_u32 s51, s39, 0
	s_add_u32 s56, s38, 0x1d6c3100
	s_addc_u32 s57, s39, 0
	s_add_u32 s58, s38, 0x1d6c3200
	s_addc_u32 s59, s39, 0
	s_mul_i32 s70, s43, s33
	s_add_u32 s60, s38, 0x1d6c3300
	s_mul_i32 s70, s70, s42
	s_addc_u32 s61, s39, 0
	s_mov_b32 s71, 1
	v_mov_b32_e32 v18, 0
	s_branch .LBB0_1459

.LBB0_1508:
	s_cmp_gt_i32 s41, 15
	s_cselect_b64 s[4:5], -1, 0
	s_and_b64 s[6:7], s[8:9], s[4:5]
	s_andn2_b64 vcc, exec, s[6:7]
	s_cbranch_vccnz .LBB0_1558
	s_waitcnt vmcnt(0)
	s_waitcnt vmcnt(0) lgkmcnt(0)
	s_barrier
	s_and_saveexec_b64 s[6:7], s[26:27]
	s_cbranch_execz .Lmy_aa_14
	s_lshl_b32 s8, s3, 8
	s_add_u32 s8, s34, s8
	s_addc_u32 s9, s35, 0
	v_mov_b32_e32 v237, 0x1000
	v_mov_b32_e32 v236, 1
	global_atomic_add v236, v237, v236, s[8:9] offset:1024 sc0
.Lmy_aa_14:
	s_or_b64 exec, exec, s[6:7]
.LBB0_1558:
	s_cmp_lt_i32 s40, 16
	s_cselect_b64 s[6:7], -1, 0
	s_and_b64 s[8:9], s[6:7], s[4:5]
	s_andn2_b64 vcc, exec, s[8:9]
	s_cbranch_vccnz .LBB0_1635
	s_waitcnt lgkmcnt(0)
	s_and_saveexec_b64 s[10:11], s[26:27]
	s_cbranch_execz .LBB0_1561
	s_add_u32 s12, s38, 0xd7c2000
	s_addc_u32 s13, s39, 0
	s_add_u32 s18, s38, 0x4d00000
	s_addc_u32 s19, s39, 0
	s_add_u32 s4, s38, 0x53c2000
	s_addc_u32 s5, s39, 0
	s_add_u32 s6, s38, 0x4900000
	s_addc_u32 s7, s39, 0
	s_add_u32 s14, s38, 0x97c2000
	s_addc_u32 s15, s39, 0
	s_add_i32 s17, 0, 0x20000
	v_mov_b64_e32 v[4:5], s[4:5]
	v_mov_b32_e32 v2, s17
	v_mov_b64_e32 v[6:7], s[6:7]
	s_add_i32 s6, 0, 0x20010
	s_mov_b32 s16, 0
	ds_write_b128 v2, v[4:7]
	v_mov_b32_e32 v2, s6
	v_mov_b64_e32 v[4:5], s[14:15]
	s_movk_i32 s17, 0x400
	s_mov_b32 s15, 8
	s_movk_i32 s14, 0x80
	s_add_i32 s6, 0, 0x20018
	ds_write_b64 v2, v[4:5]
	v_mov_b32_e32 v6, s6
	v_mov_b64_e32 v[2:3], s[14:15]
	v_mov_b64_e32 v[4:5], s[16:17]
	s_add_i32 s6, 0, 0x20028
	ds_write2_b64 v6, v[2:3], v[4:5] offset1:1
	v_mov_b32_e32 v2, 3
	v_mov_b32_e32 v3, 16
	v_mov_b32_e32 v4, s6
	ds_write_b64 v4, v[2:3]
	s_mov_b32 s6, s18
	s_mov_b32 s7, s19
	s_add_i32 s15, 0, 0x20030
	v_mov_b64_e32 v[4:5], s[4:5]
	v_mov_b32_e32 v2, s15
	v_mov_b64_e32 v[6:7], s[6:7]
	s_add_i32 s4, 0, 0x20040
	ds_write_b128 v2, v[4:7]
	v_mov_b32_e32 v2, s4
	v_mov_b64_e32 v[4:5], s[12:13]
	s_mov_b32 s15, 4
	s_mov_b32 s16, s17
	s_add_i32 s4, 0, 0x20048
	ds_write_b64 v2, v[4:5]
	v_mov_b32_e32 v2, s4
	v_mov_b64_e32 v[4:5], s[14:15]
	v_mov_b64_e32 v[6:7], s[16:17]
	s_add_i32 s4, 0, 0x20058
	ds_write2_b64 v2, v[4:5], v[6:7] offset1:1
	v_mov_b32_e32 v2, 0
	v_mov_b32_e32 v4, s4
	ds_write_b64 v4, v[2:3]
.LBB0_1561:
	s_or_b64 exec, exec, s[10:11]
	s_cmpk_lt_i32 s2, 0x600
	v_mov_b32_e32 v14, v1
	s_cselect_b64 s[4:5], -1, 0
	s_cmpk_gt_i32 s2, 0x5ff
	s_waitcnt lgkmcnt(0)
	s_barrier
	s_nop 0
	v_readfirstlane_b32 s12, v14
	s_cbranch_scc1 .LBB0_1563
	s_ashr_i32 s6, s2, 31
	s_lshr_b32 s6, s6, 29
	s_add_i32 s6, s2, s6
	s_ashr_i32 s7, s6, 3
	s_and_b32 s6, s6, -8
	s_sub_i32 s6, s2, s6
	s_cmp_lt_i32 s6, 0
	s_movk_i32 s10, 0xc1
	s_cselect_b32 s10, s10, 0xc0
	s_add_i32 s11, 0, 0x20050
	v_mov_b32_e32 v2, s11
	ds_read_b32 v2, v2
	s_mul_i32 s6, s6, s10
	s_add_i32 s6, s6, s7
	s_waitcnt lgkmcnt(0)
	v_cmp_ge_i32_e32 vcc, s6, v2
	s_nop 1
	v_cndmask_b32_e64 v2, 0, 1, vcc
	s_nop 0
	v_readfirstlane_b32 s7, v2
	s_and_b32 s56, s7, 1
	s_mul_i32 s7, s56, 48
	s_add_i32 s7, s7, 0
	s_add_i32 s7, s7, 0x20000
	v_mov_b32_e32 v4, s7
	ds_read_b64 v[2:3], v4 offset:24
	ds_read2_b32 v[140:141], v4 offset0:8 offset1:11
	s_waitcnt lgkmcnt(1)
	v_readfirstlane_b32 s7, v3
	s_lshl_b32 s7, s7, 3
	s_abs_i32 s10, s7
	v_cvt_f32_u32_e32 v3, s10
	v_readfirstlane_b32 s11, v2
	s_sub_i32 s15, 0, s10
	s_waitcnt lgkmcnt(0)
	v_readfirstlane_b32 s13, v140
	v_rcp_iflag_f32_e32 v2, v3
	s_sub_i32 s6, s6, s13
	s_abs_i32 s14, s6
	s_xor_b32 s13, s6, s7
	v_mul_f32_e32 v2, 0x4f7ffffe, v2
	v_cvt_u32_f32_e32 v2, v2
	s_ashr_i32 s13, s13, 31
	v_readfirstlane_b32 s16, v2
	s_mul_i32 s15, s15, s16
	s_mul_hi_u32 s15, s16, s15
	s_add_i32 s16, s16, s15
	s_mul_hi_u32 s15, s14, s16
	s_mul_i32 s16, s15, s10
	s_sub_i32 s14, s14, s16
	s_add_i32 s17, s15, 1
	s_sub_i32 s16, s14, s10
	s_cmp_ge_u32 s14, s10
	s_cselect_b32 s15, s17, s15
	s_cselect_b32 s14, s16, s14
	s_add_i32 s16, s15, 1
	s_cmp_ge_u32 s14, s10
	s_cselect_b32 s10, s16, s15
	s_xor_b32 s10, s10, s13
	s_sub_i32 s10, s10, s13
	s_lshl_b32 s13, s10, 3
	s_sub_i32 s11, s11, s13
	s_min_i32 s11, s11, 8
	s_abs_i32 s14, s11
	v_cvt_f32_u32_e32 v6, s14
	s_sub_i32 s15, 0, s14
	s_mul_i32 s10, s10, s7
	s_sub_i32 s6, s6, s10
	v_rcp_iflag_f32_e32 v6, v6
	s_abs_i32 s7, s6
	s_xor_b32 s10, s6, s11
	s_ashr_i32 s10, s10, 31
	v_mul_f32_e32 v6, 0x4f7ffffe, v6
	v_cvt_u32_f32_e32 v6, v6
	ds_read_b128 v[2:5], v4
	v_readfirstlane_b32 s16, v6
	s_mul_i32 s15, s15, s16
	s_mul_hi_u32 s15, s16, s15
	s_add_i32 s16, s16, s15
	s_mul_hi_u32 s15, s7, s16
	s_mul_i32 s16, s15, s14
	s_sub_i32 s7, s7, s16
	s_add_i32 s17, s15, 1
	s_sub_i32 s16, s7, s14
	s_cmp_ge_u32 s7, s14
	s_cselect_b32 s15, s17, s15
	s_cselect_b32 s7, s16, s7
	s_add_i32 s16, s15, 1
	s_cmp_ge_u32 s7, s14
	s_cselect_b32 s7, s16, s15
	s_xor_b32 s7, s7, s10
	s_sub_i32 s50, s7, s10
	s_mul_i32 s7, s50, s11
	s_sub_i32 s6, s6, s7
	s_add_i32 s6, s6, s13
	s_ashr_i32 s7, s6, 31
	s_ashr_i32 s51, s50, 31
	s_lshl_b64 s[10:11], s[6:7], 19
	s_waitcnt lgkmcnt(0)
	v_lshl_add_u64 v[2:3], v[2:3], 0, s[10:11]
	s_lshl_b64 s[10:11], s[50:51], 19
	v_lshl_add_u64 v[4:5], v[4:5], 0, s[10:11]
	s_andn2_b64 vcc, exec, s[4:5]
	s_cbranch_vccz .LBB0_1564
	s_branch .LBB0_1635

.LBB0_1635:
	s_cmp_gt_i32 s41, 16
	s_cselect_b64 s[4:5], -1, 0
	s_and_b64 s[6:7], s[8:9], s[4:5]
	s_andn2_b64 vcc, exec, s[6:7]
	s_cbranch_vccnz .LBB0_1685
	s_waitcnt vmcnt(0)
	s_waitcnt vmcnt(0) lgkmcnt(0)
	s_barrier
	s_and_saveexec_b64 s[6:7], s[26:27]
	s_cbranch_execz .LBB0_1684
	v_add_u32_e32 v239, 1, v239
	s_add_i32 s8, 0, 0x257f0
	v_mov_b32_e32 v2, s8
	s_waitcnt vmcnt(0) expcnt(0) lgkmcnt(0)
	ds_read_b32 v4, v2
	s_add_i32 s8, 0, 0x257f4
	v_mov_b32_e32 v2, s8
	ds_read_b32 v2, v2
	s_waitcnt lgkmcnt(1)
	v_cmp_ne_u32_e32 vcc, 0, v4
	s_cbranch_vccnz .LBB0_1652
	s_add_u32 s8, s38, 0x1d6c2200
	s_addc_u32 s9, s39, 0
	s_add_u32 s10, s38, 0x1d6c2400
	s_addc_u32 s11, s39, 0
	s_add_u32 s12, s38, 0x1d6c2500
	s_addc_u32 s13, s39, 0
	s_add_u32 s14, s38, 0x1d6c2600
	s_addc_u32 s15, s39, 0
	s_add_u32 s16, s38, 0x1d6c2700
	s_addc_u32 s17, s39, 0
	s_add_u32 s18, s38, 0x1d6c2800
	s_addc_u32 s19, s39, 0
	s_add_u32 s20, s38, 0x1d6c2900
	s_addc_u32 s21, s39, 0
	s_add_u32 s22, s38, 0x1d6c2a00
	s_addc_u32 s23, s39, 0
	s_add_u32 s24, s38, 0x1d6c2b00
	s_addc_u32 s25, s39, 0
	s_add_u32 s28, s38, 0x1d6c2c00
	s_addc_u32 s29, s39, 0
	s_add_u32 s44, s38, 0x1d6c2d00
	s_addc_u32 s45, s39, 0
	s_add_u32 s46, s38, 0x1d6c2e00
	s_addc_u32 s47, s39, 0
	s_add_u32 s48, s38, 0x1d6c2f00
	s_addc_u32 s49, s39, 0
	s_add_u32 s50, s38, 0x1d6c3000
	s_addc_u32 s51, s39, 0
	s_add_u32 s56, s38, 0x1d6c3100
	s_addc_u32 s57, s39, 0
	s_add_u32 s58, s38, 0x1d6c3200
	s_addc_u32 s59, s39, 0
	s_mul_i32 s70, s43, s33
	s_add_u32 s60, s38, 0x1d6c3300
	s_mul_i32 s70, s70, s42
	s_addc_u32 s61, s39, 0
	s_mov_b32 s71, 1
	v_mov_b32_e32 v18, 0
	s_branch .LBB0_1640

.LBB0_1694:
	s_cmp_gt_i32 s41, 17
	s_cselect_b64 s[0:1], -1, 0
	s_and_b64 s[4:5], s[4:5], s[0:1]
	s_andn2_b64 vcc, exec, s[4:5]
	s_cbranch_vccnz .LBB0_1744
	s_waitcnt vmcnt(0)
	s_waitcnt vmcnt(0) lgkmcnt(0)
	s_barrier
	s_and_saveexec_b64 s[4:5], s[26:27]
	s_cbranch_execz .Lmy_aa_16
	s_lshl_b32 s6, s3, 8
	s_add_u32 s6, s34, s6
	s_addc_u32 s7, s35, 0
	v_mov_b32_e32 v237, 0x1000
	v_mov_b32_e32 v236, 1
	global_atomic_add v236, v237, v236, s[6:7] offset:1024 sc0
.Lmy_aa_16:
	s_or_b64 exec, exec, s[4:5]
.LBB0_1744:
	s_cmp_lt_i32 s40, 18
	s_cselect_b64 s[4:5], -1, 0
	s_and_b64 s[6:7], s[4:5], s[0:1]
	s_andn2_b64 vcc, exec, s[6:7]
	s_cbranch_vccnz .LBB0_1825
	s_and_saveexec_b64 s[0:1], s[26:27]
	s_cbranch_execz .LBB0_1747
	s_add_u32 s4, s38, 0x152c2000
	s_addc_u32 s5, s39, 0
	s_add_u32 s8, s38, 0x4f00000
	s_addc_u32 s9, s39, 0
	s_waitcnt lgkmcnt(0)
	s_add_i32 s10, 0, 0x20000
	v_mov_b32_e32 v2, s36
	v_mov_b32_e32 v3, s37
	v_mov_b32_e32 v4, s8
	v_mov_b32_e32 v5, s9
	v_mov_b32_e32 v6, s10
	s_mov_b32 s8, 0
	ds_write_b128 v6, v[2:5]
	s_add_i32 s10, 0, 0x20010
	v_mov_b64_e32 v[4:5], s[4:5]
	s_movk_i32 s4, 0x80
	s_movk_i32 s9, 0x400
	v_mov_b32_e32 v2, s10
	s_mov_b32 s5, 4
	s_add_i32 s10, 0, 0x20018
	ds_write_b64 v2, v[4:5]
	v_mov_b32_e32 v6, s10
	v_mov_b64_e32 v[2:3], s[4:5]
	v_mov_b64_e32 v[4:5], s[8:9]
	s_add_i32 s4, 0, 0x20028
	ds_write2_b64 v6, v[2:3], v[4:5] offset1:1
	v_mov_b32_e32 v2, 4
	v_mov_b32_e32 v3, 16
	v_mov_b32_e32 v4, s4
	ds_write_b64 v4, v[2:3]
.LBB0_1747:
	s_or_b64 exec, exec, s[0:1]
	s_cmpk_lt_i32 s2, 0x200
	v_mov_b32_e32 v14, v1
	s_cselect_b64 s[0:1], -1, 0
	s_cmpk_gt_i32 s2, 0x1ff
	s_waitcnt lgkmcnt(0)
	s_barrier
	s_nop 0
	v_readfirstlane_b32 s16, v14
	s_cbranch_scc1 .LBB0_1749
	s_ashr_i32 s4, s2, 31
	s_lshr_b32 s4, s4, 29
	s_add_i32 s4, s2, s4
	s_ashr_i32 s5, s4, 3
	s_and_b32 s4, s4, -8
	s_sub_i32 s4, s2, s4
	s_lshl_b32 s8, s4, 6
	s_cmp_lt_i32 s4, 0
	s_mulk_i32 s4, 0x41
	s_cselect_b32 s4, s4, s8
	s_add_i32 s8, 0, 0x20018
	v_mov_b32_e32 v2, s8
	ds_read_b64 v[2:3], v2
	s_add_i32 s8, 0, 0x20020
	v_mov_b32_e32 v4, s8
	ds_read_b32 v4, v4
	s_add_i32 s4, s4, s5
	s_waitcnt lgkmcnt(1)
	v_readfirstlane_b32 s8, v3
	s_lshl_b32 s8, s8, 3
	s_abs_i32 s9, s8
	v_cvt_f32_u32_e32 v3, s9
	v_readfirstlane_b32 s5, v2
	s_sub_i32 s12, 0, s9
	s_waitcnt lgkmcnt(0)
	v_readfirstlane_b32 s10, v4
	v_rcp_iflag_f32_e32 v2, v3
	s_sub_i32 s4, s4, s10
	s_abs_i32 s11, s4
	s_xor_b32 s10, s4, s8
	v_mul_f32_e32 v2, 0x4f7ffffe, v2
	v_cvt_u32_f32_e32 v2, v2
	s_ashr_i32 s10, s10, 31
	v_readfirstlane_b32 s13, v2
	s_mul_i32 s12, s12, s13
	s_mul_hi_u32 s12, s13, s12
	s_add_i32 s13, s13, s12
	s_mul_hi_u32 s12, s11, s13
	s_mul_i32 s13, s12, s9
	s_sub_i32 s11, s11, s13
	s_add_i32 s13, s12, 1
	s_sub_i32 s14, s11, s9
	s_cmp_ge_u32 s11, s9
	s_cselect_b32 s12, s13, s12
	s_cselect_b32 s11, s14, s11
	s_add_i32 s13, s12, 1
	s_cmp_ge_u32 s11, s9
	s_cselect_b32 s9, s13, s12
	s_xor_b32 s9, s9, s10
	s_sub_i32 s9, s9, s10
	s_lshl_b32 s10, s9, 3
	s_sub_i32 s5, s5, s10
	s_min_i32 s5, s5, 8
	s_abs_i32 s11, s5
	v_cvt_f32_u32_e32 v2, s11
	s_sub_i32 s12, 0, s11
	s_mul_i32 s9, s9, s8
	s_sub_i32 s4, s4, s9
	v_rcp_iflag_f32_e32 v2, v2
	s_abs_i32 s8, s4
	s_xor_b32 s9, s4, s5
	s_ashr_i32 s9, s9, 31
	v_mul_f32_e32 v2, 0x4f7ffffe, v2
	v_cvt_u32_f32_e32 v2, v2
	s_nop 0
	v_readfirstlane_b32 s13, v2
	s_mul_i32 s12, s12, s13
	s_mul_hi_u32 s12, s13, s12
	s_add_i32 s13, s13, s12
	s_mul_hi_u32 s12, s8, s13
	s_mul_i32 s13, s12, s11
	s_sub_i32 s8, s8, s13
	s_add_i32 s13, s12, 1
	s_sub_i32 s14, s8, s11
	s_cmp_ge_u32 s8, s11
	s_cselect_b32 s12, s13, s12
	s_cselect_b32 s8, s14, s8
	s_add_i32 s13, s12, 1
	s_cmp_ge_u32 s8, s11
	s_cselect_b32 s8, s13, s12
	s_xor_b32 s8, s8, s9
	s_sub_i32 s46, s8, s9
	s_add_i32 s8, 0, 0x2002c
	v_mov_b32_e32 v2, s8
	s_add_i32 s8, 0, 0x20000
	v_mov_b32_e32 v3, s8
	s_mul_i32 s5, s46, s5
	ds_read_b32 v138, v2
	ds_read_b128 v[2:5], v3
	s_sub_i32 s4, s4, s5
	s_add_i32 s4, s4, s10
	s_ashr_i32 s5, s4, 31
	s_lshl_b64 s[8:9], s[4:5], 19
	s_ashr_i32 s47, s46, 31
	s_waitcnt lgkmcnt(0)
	v_lshl_add_u64 v[2:3], v[2:3], 0, s[8:9]
	s_lshl_b64 s[8:9], s[46:47], 19
	v_lshl_add_u64 v[4:5], v[4:5], 0, s[8:9]
	s_andn2_b64 vcc, exec, s[0:1]
	s_cbranch_vccz .LBB0_1750
	s_branch .LBB0_1825

.LBB0_1750:
	v_ashrrev_i32_e32 v7, 31, v14
	v_lshrrev_b32_e32 v7, 26, v7
	v_add_u32_e32 v7, v14, v7
	v_ashrrev_i32_e32 v15, 6, v7
	v_bfe_i32 v7, v14, 27, 1
	v_lshlrev_b32_e32 v6, 4, v14
	v_lshrrev_b32_e32 v7, 22, v7
	v_add_u32_e32 v7, v6, v7
	v_and_b32_e32 v7, 0xfffffc00, v7
	v_sub_u32_e32 v7, v6, v7
	v_lshrrev_b32_e32 v8, 4, v7
	v_bitop3_b32 v8, v8, v7, 32 bitop3:0x6c
	v_ashrrev_i32_e32 v7, 31, v7
	v_lshrrev_b32_e32 v7, 26, v7
	v_add_u32_e32 v7, v8, v7
	v_ashrrev_i32_e32 v16, 6, v7
	v_lshlrev_b32_e32 v9, 3, v15
	v_mul_i32_i24_e32 v10, 64, v16
	v_and_b32_e32 v9, -16, v9
	v_sub_u32_e32 v8, v8, v10
	v_mov_b32_e32 v10, 1
	v_add_u32_e32 v7, v16, v9
	v_lshlrev_b32_e32 v9, 5, v15
	v_ashrrev_i16_sdwa v8, v10, sext(v8) dst_sel:DWORD dst_unused:UNUSED_PAD src0_sel:DWORD src1_sel:BYTE_0
	v_and_b32_e32 v9, 32, v9
	v_bfe_i32 v17, v8, 0, 16
	v_and_b32_e32 v12, 3, v16
	s_mov_b32 s1, 0x1fffe0
	v_add_lshl_u32 v9, v9, v17, 1
	v_add_u32_e32 v6, 0x2000, v6
	v_lshlrev_b32_e32 v8, 1, v7
	v_lshrrev_b32_e32 v11, 2, v7
	v_and_or_b32 v12, v7, s1, v12
	v_lshl_add_u32 v130, v7, 11, v9
	v_ashrrev_i32_e32 v7, 31, v6
	v_lshrrev_b32_e32 v7, 22, v7
	v_add_u32_e32 v7, v6, v7
	v_ashrrev_i32_e32 v18, 10, v7
	v_mul_i32_i24_e32 v7, 0x400, v18
	v_sub_u32_e32 v6, v6, v7
	v_and_b32_e32 v8, 24, v8
	v_and_b32_e32 v11, 4, v11
	v_lshrrev_b32_e32 v7, 4, v6
	v_or3_b32 v8, v12, v11, v8
	v_bitop3_b32 v6, v7, v6, 32 bitop3:0x6c
	v_lshl_add_u32 v132, v8, 11, v9
	v_ashrrev_i32_e32 v8, 31, v6
	v_lshrrev_b32_e32 v8, 26, v8
	v_add_u32_e32 v8, v6, v8
	v_lshlrev_b32_e32 v7, 3, v18
	v_ashrrev_i32_e32 v19, 6, v8
	v_and_b32_e32 v8, 0xc0, v8
	v_and_b32_e32 v7, -16, v7
	v_sub_u32_e32 v6, v6, v8
	s_ashr_i32 s0, s16, 6
	v_add_u32_e32 v7, v19, v7
	v_ashrrev_i16_sdwa v6, v10, sext(v6) dst_sel:DWORD dst_unused:UNUSED_PAD src0_sel:DWORD src1_sel:BYTE_0
	v_lshlrev_b32_e32 v9, 5, v18
	v_bfe_i32 v20, v6, 0, 16
	v_lshlrev_b32_e32 v6, 1, v7
	v_lshrrev_b32_e32 v8, 2, v7
	v_and_b32_e32 v10, 3, v19
	s_lshl_b32 s23, s0, 10
	v_and_b32_e32 v9, 32, v9
	v_and_b32_e32 v6, 24, v6
	v_and_b32_e32 v8, 4, v8
	v_and_or_b32 v10, v7, s1, v10
	s_add_i32 s47, s23, 0
	v_or3_b32 v6, v10, v8, v6
	v_add_lshl_u32 v8, v9, v20, 1
	s_add_i32 m0, s47, 0x10000
	v_readfirstlane_b32 s8, v4
	v_readfirstlane_b32 s9, v5
	v_lshl_add_u32 v136, v6, 11, v8
	v_lshl_add_u32 v134, v7, 11, v8
	s_add_i32 s56, s47, 0x2000
	s_add_i32 s57, s47, 0x4000
	s_add_i32 s58, s47, 0x6000
	s_and_saveexec_b64 s[96:97], s[26:27]
	s_cbranch_execz .Lmy_w_16
	v_mov_b32_e32 v238, 0x257f0
	ds_read2_b32 v[234:235], v238 offset1:1
	v_add_u32_e32 v239, 1, v239
	s_add_u32 s98, s38, 0x1d6c5400
	s_addc_u32 s99, s39, 0
	s_mov_b32 s94, 0
	s_waitcnt vmcnt(0) lgkmcnt(0)
	v_mul_u32_u24_e32 v238, v239, v234
	v_add_u32_e32 v236, 1, v236
	v_mul_u32_u24_e32 v237, v239, v235
	v_cmp_eq_u32_e32 vcc, v236, v238
	v_mov_b32_e32 v238, 0
	s_cbranch_vccz .Lmy_ws_16
	buffer_wbl2 sc1
	s_waitcnt vmcnt(0)
	v_mov_b32_e32 v234, 0x1d6c5000
	v_mov_b32_e32 v235, 1
	global_atomic_add v234, v235, s[38:39] offset:1024

.LBB0_1825:
	s_cmp_gt_i32 s41, 18
	s_cselect_b64 s[0:1], -1, 0
	s_and_b64 s[4:5], s[6:7], s[0:1]
	s_andn2_b64 vcc, exec, s[4:5]
	s_cbranch_vccnz .LBB0_1875
	s_waitcnt vmcnt(0)
	s_waitcnt vmcnt(0) lgkmcnt(0)
	s_barrier
	s_and_saveexec_b64 s[4:5], s[26:27]
	s_cbranch_execz .LBB0_1874
	v_add_u32_e32 v239, 1, v239
	s_add_i32 s6, 0, 0x257f0
	v_mov_b32_e32 v2, s6
	s_waitcnt vmcnt(0) expcnt(0) lgkmcnt(0)
	ds_read_b32 v4, v2
	s_add_i32 s6, 0, 0x257f4
	v_mov_b32_e32 v2, s6
	ds_read_b32 v2, v2
	s_waitcnt lgkmcnt(1)
	v_cmp_ne_u32_e32 vcc, 0, v4
	s_cbranch_vccnz .LBB0_1842
	s_add_u32 s6, s38, 0x1d6c2200
	s_addc_u32 s7, s39, 0
	s_add_u32 s8, s38, 0x1d6c2400
	s_addc_u32 s9, s39, 0
	s_add_u32 s10, s38, 0x1d6c2500
	s_addc_u32 s11, s39, 0
	s_add_u32 s12, s38, 0x1d6c2600
	s_addc_u32 s13, s39, 0
	s_add_u32 s14, s38, 0x1d6c2700
	s_addc_u32 s15, s39, 0
	s_add_u32 s16, s38, 0x1d6c2800
	s_addc_u32 s17, s39, 0
	s_add_u32 s18, s38, 0x1d6c2900
	s_addc_u32 s19, s39, 0
	s_add_u32 s20, s38, 0x1d6c2a00
	s_addc_u32 s21, s39, 0
	s_add_u32 s22, s38, 0x1d6c2b00
	s_addc_u32 s23, s39, 0
	s_add_u32 s24, s38, 0x1d6c2c00
	s_addc_u32 s25, s39, 0
	s_add_u32 s28, s38, 0x1d6c2d00
	s_addc_u32 s29, s39, 0
	s_add_u32 s44, s38, 0x1d6c2e00
	s_addc_u32 s45, s39, 0
	s_add_u32 s46, s38, 0x1d6c2f00
	s_addc_u32 s47, s39, 0
	s_add_u32 s48, s38, 0x1d6c3000
	s_addc_u32 s49, s39, 0
	s_add_u32 s50, s38, 0x1d6c3100
	s_addc_u32 s51, s39, 0
	s_add_u32 s56, s38, 0x1d6c3200
	s_addc_u32 s57, s39, 0
	s_mul_i32 s66, s43, s33
	s_add_u32 s58, s38, 0x1d6c3300
	s_mul_i32 s66, s66, s42
	s_addc_u32 s59, s39, 0
	s_mov_b32 s67, 1
	v_mov_b32_e32 v18, 0
	s_branch .LBB0_1830

.LBB0_1879:
	s_cmp_gt_i32 s41, 19
	s_cselect_b64 s[0:1], -1, 0
	s_and_b64 s[4:5], s[6:7], s[0:1]
	s_andn2_b64 vcc, exec, s[4:5]
	s_cbranch_vccnz .LBB0_1929
	s_waitcnt vmcnt(0)
	s_waitcnt vmcnt(0) lgkmcnt(0)
	s_barrier
	s_and_saveexec_b64 s[4:5], s[26:27]
	s_cbranch_execz .Lmy_aa_18
	s_lshl_b32 s6, s3, 8
	s_add_u32 s6, s34, s6
	s_addc_u32 s7, s35, 0
	v_mov_b32_e32 v237, 0x1000
	v_mov_b32_e32 v236, 1
	global_atomic_add v236, v237, v236, s[6:7] offset:1024 sc0
.Lmy_aa_18:
	s_or_b64 exec, exec, s[4:5]
.LBB0_1929:
	s_cmp_lt_i32 s40, 20
	s_cselect_b64 s[4:5], -1, 0
	s_and_b64 s[6:7], s[4:5], s[0:1]
	s_andn2_b64 vcc, exec, s[6:7]
	s_cbranch_vccnz .LBB0_2006
	s_and_saveexec_b64 s[0:1], s[26:27]
	s_cbranch_execz .LBB0_1932
	s_add_u32 s8, s38, 0x53c2000
	s_addc_u32 s9, s39, 0
	s_waitcnt lgkmcnt(0)
	s_add_u32 s10, s38, 0x2100000
	s_addc_u32 s11, s39, 0
	s_add_u32 s4, s38, 0x97c2000
	s_addc_u32 s5, s39, 0
	v_mov_b32_e32 v4, s10
	s_add_i32 s10, 0, 0x20000
	v_mov_b32_e32 v2, s8
	v_mov_b32_e32 v3, s9
	v_mov_b32_e32 v5, s11
	v_mov_b32_e32 v6, s10
	s_mov_b32 s8, 0
	ds_write_b128 v6, v[2:5]
	s_add_i32 s10, 0, 0x20010
	v_mov_b64_e32 v[4:5], s[4:5]
	s_movk_i32 s4, 0x80
	s_movk_i32 s9, 0xb00
	v_mov_b32_e32 v2, s10
	s_mov_b32 s5, 22
	s_add_i32 s10, 0, 0x20018
	ds_write_b64 v2, v[4:5]
	v_mov_b32_e32 v6, s10
	v_mov_b64_e32 v[2:3], s[4:5]
	v_mov_b64_e32 v[4:5], s[8:9]
	s_add_i32 s4, 0, 0x20028
	ds_write2_b64 v6, v[2:3], v[4:5] offset1:1
	v_mov_b32_e32 v2, 1
	v_mov_b32_e32 v3, 16
	v_mov_b32_e32 v4, s4
	ds_write_b64 v4, v[2:3]
.LBB0_1932:
	s_or_b64 exec, exec, s[0:1]
	s_cmpk_lt_i32 s2, 0xb00
	v_mov_b32_e32 v14, v1
	s_cselect_b64 s[0:1], -1, 0
	s_cmpk_gt_i32 s2, 0xaff
	s_waitcnt lgkmcnt(0)
	s_barrier
	s_nop 0
	v_readfirstlane_b32 s10, v14
	s_cbranch_scc1 .LBB0_1934
	s_ashr_i32 s4, s2, 31
	s_lshr_b32 s4, s4, 29
	s_add_i32 s4, s2, s4
	s_ashr_i32 s5, s4, 3
	s_and_b32 s4, s4, -8
	s_sub_i32 s4, s2, s4
	s_cmp_lt_i32 s4, 0
	s_movk_i32 s8, 0x161
	s_cselect_b32 s8, s8, 0x160
	s_add_i32 s9, 0, 0x20018
	v_mov_b32_e32 v2, s9
	ds_read_b64 v[2:3], v2
	s_add_i32 s9, 0, 0x20020
	v_mov_b32_e32 v4, s9
	ds_read_b32 v4, v4
	s_mul_i32 s4, s4, s8
	s_waitcnt lgkmcnt(1)
	v_readfirstlane_b32 s9, v3
	s_lshl_b32 s9, s9, 3
	s_abs_i32 s11, s9
	v_cvt_f32_u32_e32 v3, s11
	s_add_i32 s4, s4, s5
	v_readfirstlane_b32 s5, v2
	s_sub_i32 s13, 0, s11
	v_rcp_iflag_f32_e32 v2, v3
	s_waitcnt lgkmcnt(0)
	v_readfirstlane_b32 s8, v4
	s_sub_i32 s4, s4, s8
	s_abs_i32 s12, s4
	v_mul_f32_e32 v2, 0x4f7ffffe, v2
	v_cvt_u32_f32_e32 v2, v2
	s_xor_b32 s8, s4, s9
	s_ashr_i32 s8, s8, 31
	v_readfirstlane_b32 s14, v2
	s_mul_i32 s13, s13, s14
	s_mul_hi_u32 s13, s14, s13
	s_add_i32 s14, s14, s13
	s_mul_hi_u32 s13, s12, s14
	s_mul_i32 s14, s13, s11
	s_sub_i32 s12, s12, s14
	s_add_i32 s14, s13, 1
	s_sub_i32 s15, s12, s11
	s_cmp_ge_u32 s12, s11
	s_cselect_b32 s13, s14, s13
	s_cselect_b32 s12, s15, s12
	s_add_i32 s14, s13, 1
	s_cmp_ge_u32 s12, s11
	s_cselect_b32 s11, s14, s13
	s_xor_b32 s11, s11, s8
	s_sub_i32 s8, s11, s8
	s_lshl_b32 s11, s8, 3
	s_sub_i32 s5, s5, s11
	s_min_i32 s5, s5, 8
	s_abs_i32 s12, s5
	v_cvt_f32_u32_e32 v2, s12
	s_sub_i32 s13, 0, s12
	s_mul_i32 s8, s8, s9
	s_sub_i32 s4, s4, s8
	v_rcp_iflag_f32_e32 v2, v2
	s_abs_i32 s9, s4
	s_xor_b32 s8, s4, s5
	s_ashr_i32 s8, s8, 31
	v_mul_f32_e32 v2, 0x4f7ffffe, v2
	v_cvt_u32_f32_e32 v2, v2
	s_nop 0
	v_readfirstlane_b32 s14, v2
	s_mul_i32 s13, s13, s14
	s_mul_hi_u32 s13, s14, s13
	s_add_i32 s14, s14, s13
	s_mul_hi_u32 s13, s9, s14
	s_mul_i32 s14, s13, s12
	s_sub_i32 s9, s9, s14
	s_add_i32 s14, s13, 1
	s_sub_i32 s15, s9, s12
	s_cmp_ge_u32 s9, s12
	s_cselect_b32 s13, s14, s13
	s_cselect_b32 s9, s15, s9
	s_add_i32 s14, s13, 1
	s_cmp_ge_u32 s9, s12
	s_cselect_b32 s9, s14, s13
	s_xor_b32 s9, s9, s8
	s_sub_i32 s48, s9, s8
	s_add_i32 s8, 0, 0x2002c
	v_mov_b32_e32 v2, s8
	s_add_i32 s8, 0, 0x20000
	v_mov_b32_e32 v3, s8
	s_mul_i32 s5, s48, s5
	ds_read_b32 v138, v2
	ds_read_b128 v[2:5], v3
	s_sub_i32 s4, s4, s5
	s_add_i32 s4, s4, s11
	s_ashr_i32 s5, s4, 31
	s_lshl_b64 s[8:9], s[4:5], 19
	s_ashr_i32 s49, s48, 31
	s_waitcnt lgkmcnt(0)
	v_lshl_add_u64 v[2:3], v[2:3], 0, s[8:9]
	s_lshl_b64 s[8:9], s[48:49], 19
	v_lshl_add_u64 v[4:5], v[4:5], 0, s[8:9]
	s_andn2_b64 vcc, exec, s[0:1]
	s_cbranch_vccz .LBB0_1935
	s_branch .LBB0_2006

.LBB0_1935:
	v_ashrrev_i32_e32 v7, 31, v14
	v_lshrrev_b32_e32 v7, 26, v7
	v_add_u32_e32 v7, v14, v7
	v_ashrrev_i32_e32 v15, 6, v7
	v_bfe_i32 v7, v14, 27, 1
	v_lshlrev_b32_e32 v6, 4, v14
	v_lshrrev_b32_e32 v7, 22, v7
	v_add_u32_e32 v7, v6, v7
	v_and_b32_e32 v7, 0xfffffc00, v7
	v_sub_u32_e32 v7, v6, v7
	v_lshrrev_b32_e32 v8, 4, v7
	v_bitop3_b32 v8, v8, v7, 32 bitop3:0x6c
	v_ashrrev_i32_e32 v7, 31, v7
	v_lshrrev_b32_e32 v7, 26, v7
	v_add_u32_e32 v7, v8, v7
	v_ashrrev_i32_e32 v16, 6, v7
	v_lshlrev_b32_e32 v9, 3, v15
	v_mul_i32_i24_e32 v10, 64, v16
	v_and_b32_e32 v9, -16, v9
	v_sub_u32_e32 v8, v8, v10
	v_mov_b32_e32 v10, 1
	v_add_u32_e32 v7, v16, v9
	v_lshlrev_b32_e32 v9, 5, v15
	v_ashrrev_i16_sdwa v8, v10, sext(v8) dst_sel:DWORD dst_unused:UNUSED_PAD src0_sel:DWORD src1_sel:BYTE_0
	v_and_b32_e32 v9, 32, v9
	v_bfe_i32 v17, v8, 0, 16
	v_and_b32_e32 v12, 3, v16
	s_mov_b32 s1, 0x1fffe0
	v_add_lshl_u32 v9, v9, v17, 1
	v_add_u32_e32 v6, 0x2000, v6
	v_lshlrev_b32_e32 v8, 1, v7
	v_lshrrev_b32_e32 v11, 2, v7
	v_and_or_b32 v12, v7, s1, v12
	v_lshl_add_u32 v130, v7, 11, v9
	v_ashrrev_i32_e32 v7, 31, v6
	v_lshrrev_b32_e32 v7, 22, v7
	v_add_u32_e32 v7, v6, v7
	v_ashrrev_i32_e32 v18, 10, v7
	v_mul_i32_i24_e32 v7, 0x400, v18
	v_sub_u32_e32 v6, v6, v7
	v_and_b32_e32 v8, 24, v8
	v_and_b32_e32 v11, 4, v11
	v_lshrrev_b32_e32 v7, 4, v6
	v_or3_b32 v8, v12, v11, v8
	v_bitop3_b32 v6, v7, v6, 32 bitop3:0x6c
	v_lshl_add_u32 v132, v8, 11, v9
	v_ashrrev_i32_e32 v8, 31, v6
	v_lshrrev_b32_e32 v8, 26, v8
	v_add_u32_e32 v8, v6, v8
	v_lshlrev_b32_e32 v7, 3, v18
	v_ashrrev_i32_e32 v19, 6, v8
	v_and_b32_e32 v8, 0xc0, v8
	v_and_b32_e32 v7, -16, v7
	v_sub_u32_e32 v6, v6, v8
	s_ashr_i32 s0, s10, 6
	v_add_u32_e32 v7, v19, v7
	v_ashrrev_i16_sdwa v6, v10, sext(v6) dst_sel:DWORD dst_unused:UNUSED_PAD src0_sel:DWORD src1_sel:BYTE_0
	v_lshlrev_b32_e32 v9, 5, v18
	v_bfe_i32 v20, v6, 0, 16
	v_lshlrev_b32_e32 v6, 1, v7
	v_lshrrev_b32_e32 v8, 2, v7
	v_and_b32_e32 v10, 3, v19
	s_lshl_b32 s25, s0, 10
	v_and_b32_e32 v9, 32, v9
	v_and_b32_e32 v6, 24, v6
	v_and_b32_e32 v8, 4, v8
	v_and_or_b32 v10, v7, s1, v10
	s_add_i32 s49, s25, 0
	v_or3_b32 v6, v10, v8, v6
	v_add_lshl_u32 v8, v9, v20, 1
	s_add_i32 m0, s49, 0x10000
	v_readfirstlane_b32 s8, v4
	v_readfirstlane_b32 s9, v5
	v_lshl_add_u32 v136, v6, 11, v8
	v_lshl_add_u32 v134, v7, 11, v8
	s_add_i32 s58, s49, 0x2000
	s_add_i32 s59, s49, 0x4000
	s_add_i32 s60, s49, 0x6000
	s_and_saveexec_b64 s[96:97], s[26:27]
	s_cbranch_execz .Lmy_w_18
	v_mov_b32_e32 v238, 0x257f0
	ds_read2_b32 v[234:235], v238 offset1:1
	v_add_u32_e32 v239, 1, v239
	s_add_u32 s98, s38, 0x1d6c5400
	s_addc_u32 s99, s39, 0
	s_mov_b32 s94, 0
	s_waitcnt vmcnt(0) lgkmcnt(0)
	v_mul_u32_u24_e32 v238, v239, v234
	v_add_u32_e32 v236, 1, v236
	v_mul_u32_u24_e32 v237, v239, v235
	v_cmp_eq_u32_e32 vcc, v236, v238
	v_mov_b32_e32 v238, 0
	s_cbranch_vccz .Lmy_ws_18
	buffer_wbl2 sc1
	s_waitcnt vmcnt(0)
	v_mov_b32_e32 v234, 0x1d6c5000
	v_mov_b32_e32 v235, 1
	global_atomic_add v234, v235, s[38:39] offset:1024

.LBB0_2006:
	s_cmp_gt_i32 s41, 20
	s_cselect_b64 s[0:1], -1, 0
	s_and_b64 s[4:5], s[6:7], s[0:1]
	s_andn2_b64 vcc, exec, s[4:5]
	s_cbranch_vccnz .LBB0_2056
	s_waitcnt vmcnt(0)
	s_waitcnt vmcnt(0) lgkmcnt(0)
	s_barrier
	s_and_saveexec_b64 s[4:5], s[26:27]
	s_cbranch_execz .Lmy_aa_19
	s_lshl_b32 s6, s3, 8
	s_add_u32 s6, s34, s6
	s_addc_u32 s7, s35, 0
	v_mov_b32_e32 v237, 0x1000
	v_mov_b32_e32 v236, 1
	global_atomic_add v236, v237, v236, s[6:7] offset:1024 sc0
.Lmy_aa_19:
	s_or_b64 exec, exec, s[4:5]
.LBB0_2056:
	s_cmp_lt_i32 s40, 21
	s_cselect_b64 s[4:5], -1, 0
	s_and_b64 s[6:7], s[4:5], s[0:1]
	s_andn2_b64 vcc, exec, s[6:7]
	s_cbranch_vccnz .LBB0_2137
	s_and_saveexec_b64 s[0:1], s[26:27]
	s_cbranch_execz .LBB0_2059
	s_add_u32 s4, s38, 0x152c2000
	s_addc_u32 s5, s39, 0
	s_add_u32 s8, s38, 0x97c2000
	s_addc_u32 s9, s39, 0
	s_waitcnt lgkmcnt(0)
	s_add_u32 s10, s38, 0x3c80000
	s_addc_u32 s11, s39, 0
	v_mov_b32_e32 v4, s10
	s_add_i32 s10, 0, 0x20000
	v_mov_b32_e32 v2, s8
	v_mov_b32_e32 v3, s9
	v_mov_b32_e32 v5, s11
	v_mov_b32_e32 v6, s10
	s_mov_b32 s8, 0
	ds_write_b128 v6, v[2:5]
	s_add_i32 s10, 0, 0x20010
	v_mov_b64_e32 v[4:5], s[4:5]
	s_movk_i32 s4, 0x80
	s_movk_i32 s9, 0x400
	v_mov_b32_e32 v2, s10
	s_mov_b32 s5, 4
	s_add_i32 s10, 0, 0x20018
	ds_write_b64 v2, v[4:5]
	v_mov_b32_e32 v6, s10
	v_mov_b64_e32 v[2:3], s[4:5]
	v_mov_b64_e32 v[4:5], s[8:9]
	s_add_i32 s4, 0, 0x20028
	ds_write2_b64 v6, v[2:3], v[4:5] offset1:1
	v_mov_b32_e32 v2, 4
	v_mov_b32_e32 v3, 44
	v_mov_b32_e32 v4, s4
	ds_write_b64 v4, v[2:3]
.LBB0_2059:
	s_or_b64 exec, exec, s[0:1]
	s_cmpk_lt_i32 s2, 0x200
	v_mov_b32_e32 v12, v1
	s_cselect_b64 s[0:1], -1, 0
	s_cmpk_gt_i32 s2, 0x1ff
	s_waitcnt lgkmcnt(0)
	s_barrier
	s_nop 0
	v_readfirstlane_b32 s4, v12
	s_cbranch_scc1 .LBB0_2061
	s_ashr_i32 s5, s2, 31
	s_lshr_b32 s5, s5, 29
	s_add_i32 s5, s2, s5
	s_ashr_i32 s8, s5, 3
	s_and_b32 s5, s5, -8
	s_sub_i32 s5, s2, s5
	s_lshl_b32 s9, s5, 6
	s_cmp_lt_i32 s5, 0
	s_mulk_i32 s5, 0x41
	s_cselect_b32 s5, s5, s9
	s_add_i32 s9, 0, 0x20018
	v_mov_b32_e32 v2, s9
	ds_read_b64 v[2:3], v2
	s_add_i32 s9, 0, 0x20020
	v_mov_b32_e32 v4, s9
	ds_read_b32 v4, v4
	s_add_i32 s5, s5, s8
	s_waitcnt lgkmcnt(1)
	v_readfirstlane_b32 s9, v3
	s_lshl_b32 s9, s9, 3
	s_abs_i32 s10, s9
	v_cvt_f32_u32_e32 v3, s10
	v_readfirstlane_b32 s8, v2
	s_sub_i32 s13, 0, s10
	s_waitcnt lgkmcnt(0)
	v_readfirstlane_b32 s11, v4
	v_rcp_iflag_f32_e32 v2, v3
	s_sub_i32 s5, s5, s11
	s_abs_i32 s12, s5
	s_xor_b32 s11, s5, s9
	v_mul_f32_e32 v2, 0x4f7ffffe, v2
	v_cvt_u32_f32_e32 v2, v2
	s_ashr_i32 s11, s11, 31
	v_readfirstlane_b32 s14, v2
	s_mul_i32 s13, s13, s14
	s_mul_hi_u32 s13, s14, s13
	s_add_i32 s14, s14, s13
	s_mul_hi_u32 s13, s12, s14
	s_mul_i32 s14, s13, s10
	s_sub_i32 s12, s12, s14
	s_add_i32 s14, s13, 1
	s_sub_i32 s15, s12, s10
	s_cmp_ge_u32 s12, s10
	s_cselect_b32 s13, s14, s13
	s_cselect_b32 s12, s15, s12
	s_add_i32 s14, s13, 1
	s_cmp_ge_u32 s12, s10
	s_cselect_b32 s10, s14, s13
	s_xor_b32 s10, s10, s11
	s_sub_i32 s10, s10, s11
	s_lshl_b32 s11, s10, 3
	s_sub_i32 s8, s8, s11
	s_min_i32 s8, s8, 8
	s_abs_i32 s12, s8
	v_cvt_f32_u32_e32 v2, s12
	s_sub_i32 s13, 0, s12
	s_mul_i32 s10, s10, s9
	s_sub_i32 s5, s5, s10
	v_rcp_iflag_f32_e32 v2, v2
	s_abs_i32 s9, s5
	s_xor_b32 s10, s5, s8
	s_ashr_i32 s10, s10, 31
	v_mul_f32_e32 v2, 0x4f7ffffe, v2
	v_cvt_u32_f32_e32 v2, v2
	s_nop 0
	v_readfirstlane_b32 s14, v2
	s_mul_i32 s13, s13, s14
	s_mul_hi_u32 s13, s14, s13
	s_add_i32 s14, s14, s13
	s_mul_hi_u32 s13, s9, s14
	s_mul_i32 s14, s13, s12
	s_sub_i32 s9, s9, s14
	s_add_i32 s14, s13, 1
	s_sub_i32 s15, s9, s12
	s_cmp_ge_u32 s9, s12
	s_cselect_b32 s13, s14, s13
	s_cselect_b32 s9, s15, s9
	s_add_i32 s14, s13, 1
	s_cmp_ge_u32 s9, s12
	s_cselect_b32 s9, s14, s13
	s_xor_b32 s9, s9, s10
	s_sub_i32 s74, s9, s10
	s_add_i32 s9, 0, 0x2002c
	v_mov_b32_e32 v2, s9
	s_add_i32 s9, 0, 0x20000
	v_mov_b32_e32 v3, s9
	ds_read_b32 v156, v2
	ds_read_b128 v[2:5], v3
	s_mul_i32 s8, s74, s8
	s_sub_i32 s5, s5, s8
	s_add_i32 s24, s5, s11
	s_mul_hi_i32 s9, s24, 0x160000
	s_mul_i32 s8, s24, 0x160000
	s_waitcnt lgkmcnt(0)
	v_lshl_add_u64 v[150:151], v[2:3], 0, s[8:9]
	s_mul_hi_i32 s9, s74, 0x160000
	s_mul_i32 s8, s74, 0x160000
	v_lshl_add_u64 v[2:3], v[4:5], 0, s[8:9]
	s_andn2_b64 vcc, exec, s[0:1]
	s_cbranch_vccz .LBB0_2062
	s_branch .LBB0_2137

.LBB0_2062:
	v_ashrrev_i32_e32 v5, 31, v12
	v_lshrrev_b32_e32 v5, 26, v5
	v_add_u32_e32 v5, v12, v5
	v_ashrrev_i32_e32 v13, 6, v5
	v_bfe_i32 v5, v12, 27, 1
	v_lshlrev_b32_e32 v4, 4, v12
	v_lshrrev_b32_e32 v5, 22, v5
	v_add_u32_e32 v5, v4, v5
	v_and_b32_e32 v5, 0xfffffc00, v5
	v_sub_u32_e32 v5, v4, v5
	v_lshrrev_b32_e32 v6, 4, v5
	v_bitop3_b32 v6, v6, v5, 32 bitop3:0x6c
	v_ashrrev_i32_e32 v5, 31, v5
	v_lshrrev_b32_e32 v5, 26, v5
	v_lshlrev_b32_e32 v7, 3, v13
	v_add_u32_e32 v5, v6, v5
	v_and_b32_e32 v7, -16, v7
	v_ashrrev_i32_e32 v14, 6, v5
	v_add_u32_e32 v5, v14, v7
	v_lshlrev_b32_e32 v7, 5, v13
	v_and_b32_e32 v15, 32, v7
	v_mul_i32_i24_e32 v7, 64, v14
	v_sub_u32_e32 v6, v6, v7
	v_mov_b32_e32 v7, 1
	v_ashrrev_i16_sdwa v6, v7, sext(v6) dst_sel:DWORD dst_unused:UNUSED_PAD src0_sel:DWORD src1_sel:BYTE_0
	v_lshlrev_b32_e32 v8, 1, v5
	v_lshrrev_b32_e32 v9, 2, v5
	v_and_b32_e32 v10, 3, v14
	s_mov_b32 s1, 0xffffe0
	v_bfe_i32 v16, v6, 0, 16
	v_and_b32_e32 v8, 24, v8
	v_and_b32_e32 v9, 4, v9
	v_and_or_b32 v10, v5, s1, v10
	s_movk_i32 s5, 0xb00
	v_add_u32_e32 v6, v15, v16
	v_or3_b32 v8, v10, v9, v8
	v_mul_lo_u32 v5, v5, s5
	v_add_lshl_u32 v130, v6, v5, 1
	v_mul_u32_u24_e32 v5, 0xb00, v8
	v_add_u32_e32 v4, 0x2000, v4
	v_add_lshl_u32 v132, v5, v6, 1
	v_ashrrev_i32_e32 v5, 31, v4
	v_lshrrev_b32_e32 v5, 22, v5
	v_add_u32_e32 v5, v4, v5
	v_ashrrev_i32_e32 v17, 10, v5
	v_mul_i32_i24_e32 v5, 0x400, v17
	v_sub_u32_e32 v4, v4, v5
	v_lshrrev_b32_e32 v5, 4, v4
	v_bitop3_b32 v4, v5, v4, 32 bitop3:0x6c
	v_ashrrev_i32_e32 v6, 31, v4
	v_lshrrev_b32_e32 v6, 26, v6
	v_lshlrev_b32_e32 v5, 3, v17
	v_add_u32_e32 v6, v4, v6
	v_and_b32_e32 v5, -16, v5
	v_ashrrev_i32_e32 v19, 6, v6
	v_and_b32_e32 v6, 0xc0, v6
	v_add_u32_e32 v5, v19, v5
	v_lshlrev_b32_e32 v8, 5, v17
	v_sub_u32_e32 v4, v4, v6
	s_ashr_i32 s0, s4, 6
	v_and_b32_e32 v18, 32, v8
	v_ashrrev_i16_sdwa v4, v7, sext(v4) dst_sel:DWORD dst_unused:UNUSED_PAD src0_sel:DWORD src1_sel:BYTE_0
	v_lshlrev_b32_e32 v6, 1, v5
	v_lshrrev_b32_e32 v7, 2, v5
	v_and_b32_e32 v8, 3, v19
	v_bfe_i32 v20, v4, 0, 16
	v_and_b32_e32 v6, 24, v6
	v_and_b32_e32 v7, 4, v7
	v_and_or_b32 v8, v5, s1, v8
	s_lshl_b32 s21, s0, 10
	v_add_u32_e32 v4, v18, v20
	v_or3_b32 v6, v8, v7, v6
	v_mul_lo_u32 v5, v5, s5
	s_add_i32 s44, s21, 0
	v_add_lshl_u32 v134, v4, v5, 1
	v_mul_u32_u24_e32 v5, 0xb00, v6
	s_add_i32 m0, s44, 0x10000
	v_readfirstlane_b32 s8, v2
	v_readfirstlane_b32 s9, v3
	v_add_lshl_u32 v136, v5, v4, 1
	s_add_i32 s45, s44, 0x2000
	s_add_i32 s46, s44, 0x4000
	s_add_i32 s47, s44, 0x6000
	s_ashr_i32 s1, s4, 8
	s_and_saveexec_b64 s[96:97], s[26:27]
	s_cbranch_execz .Lmy_w_19
	v_mov_b32_e32 v238, 0x257f0
	ds_read2_b32 v[234:235], v238 offset1:1
	v_add_u32_e32 v239, 1, v239
	s_add_u32 s98, s38, 0x1d6c5400
	s_addc_u32 s99, s39, 0
	s_mov_b32 s94, 0
	s_waitcnt vmcnt(0) lgkmcnt(0)
	v_mul_u32_u24_e32 v238, v239, v234
	v_add_u32_e32 v236, 1, v236
	v_mul_u32_u24_e32 v237, v239, v235
	v_cmp_eq_u32_e32 vcc, v236, v238
	v_mov_b32_e32 v238, 0
	s_cbranch_vccz .Lmy_ws_19
	buffer_wbl2 sc1
	s_waitcnt vmcnt(0)
	v_mov_b32_e32 v234, 0x1d6c5000
	v_mov_b32_e32 v235, 1
	global_atomic_add v234, v235, s[38:39] offset:1024

.LBB0_2137:
	s_cmp_gt_i32 s41, 21
	s_cselect_b64 s[0:1], -1, 0
	s_and_b64 s[4:5], s[6:7], s[0:1]
	s_andn2_b64 vcc, exec, s[4:5]
	s_cbranch_vccnz .LBB0_2187
	s_waitcnt vmcnt(0)
	s_waitcnt vmcnt(0) lgkmcnt(0)
	s_barrier
	s_and_saveexec_b64 s[4:5], s[26:27]
	s_cbranch_execz .LBB0_2186
	v_add_u32_e32 v239, 1, v239
	s_add_i32 s6, 0, 0x257f0
	v_mov_b32_e32 v2, s6
	s_waitcnt vmcnt(0) expcnt(0) lgkmcnt(0)
	ds_read_b32 v4, v2
	s_add_i32 s6, 0, 0x257f4
	v_mov_b32_e32 v2, s6
	ds_read_b32 v2, v2
	s_waitcnt lgkmcnt(1)
	v_cmp_ne_u32_e32 vcc, 0, v4
	s_cbranch_vccnz .LBB0_2154
	s_add_u32 s6, s38, 0x1d6c2200
	s_addc_u32 s7, s39, 0
	s_add_u32 s8, s38, 0x1d6c2400
	s_addc_u32 s9, s39, 0
	s_add_u32 s10, s38, 0x1d6c2500
	s_addc_u32 s11, s39, 0
	s_add_u32 s12, s38, 0x1d6c2600
	s_addc_u32 s13, s39, 0
	s_add_u32 s14, s38, 0x1d6c2700
	s_addc_u32 s15, s39, 0
	s_add_u32 s16, s38, 0x1d6c2800
	s_addc_u32 s17, s39, 0
	s_add_u32 s18, s38, 0x1d6c2900
	s_addc_u32 s19, s39, 0
	s_add_u32 s20, s38, 0x1d6c2a00
	s_addc_u32 s21, s39, 0
	s_add_u32 s22, s38, 0x1d6c2b00
	s_addc_u32 s23, s39, 0
	s_add_u32 s24, s38, 0x1d6c2c00
	s_addc_u32 s25, s39, 0
	s_add_u32 s26, s38, 0x1d6c2d00
	s_addc_u32 s27, s39, 0
	s_add_u32 s28, s38, 0x1d6c2e00
	s_addc_u32 s29, s39, 0
	s_add_u32 s44, s38, 0x1d6c2f00
	s_addc_u32 s45, s39, 0
	s_add_u32 s46, s38, 0x1d6c3000
	s_addc_u32 s47, s39, 0
	s_add_u32 s48, s38, 0x1d6c3100
	s_addc_u32 s49, s39, 0
	s_add_u32 s50, s38, 0x1d6c3200
	s_addc_u32 s51, s39, 0
	s_mul_i32 s33, s43, s33
	s_add_u32 s56, s38, 0x1d6c3300
	s_mul_i32 s33, s33, s42
	s_addc_u32 s57, s39, 0
	s_mov_b32 s43, 1
	v_mov_b32_e32 v18, 0
	s_branch .LBB0_2142
